# residual GEMM epilogues rewritten (tile-uniform scalars, pipelined X loads), adaLN gemv loads batched, R7_CA S0 operands shared through LDS
# speedup vs baseline: 1.1673x; 1.0401x over previous
; #define PG8_STAGE(bufoff, gbase, voff) do { _Pragma("unroll") for (int _i = 0; _i < 2; ++_i) \
;     __builtin_amdgcn_global_load_lds((const unsigned*)((const char*)(gbase) + (voff)[_i]), (PG8_LAS unsigned*)(lds + (bufoff) + ldsw + _i * 8192), 16, 0, 0); } while (0)
; #define PG8_LDA(dst, b, h) do { _Pragma("unroll") for (int m = 0; m < 4; ++m) _Pragma("unroll") for (int k = 0; k < 2; ++k) dst[m][k] = *(const PG8_LAS bf16x8*)(lds + PG8_SA(b, h) + aoff + m * 2048 + k * 1024); } while (0)
; #define PG8_LDB(dst, b, h) do { _Pragma("unroll") for (int n = 0; n < 2; ++n) _Pragma("unroll") for (int k = 0; k < 2; ++k) dst[n][k] = *(const PG8_LAS bf16x8*)(lds + PG8_SB(b, h) + boff + n * 2048 + k * 1024); } while (0)
; #define PG8_MMA(ai, bj, At, Bt) do { __builtin_amdgcn_s_setprio(1); _Pragma("unroll") for (int m = 0; m < 4; ++m) _Pragma("unroll") for (int n = 0; n < 2; ++n) _Pragma("unroll") for (int k = 0; k < 2; ++k) \
;     acc[ai][bj][m][n] = __builtin_amdgcn_mfma_f32_16x16x32_bf16(Bt[n][k], At[m][k], acc[ai][bj][m][n], 0, 0, 0); __builtin_amdgcn_s_setprio(0); } while (0)
; #define PG8_WAIT_V(n) asm volatile("s_waitcnt vmcnt(" #n ")" ::: "memory")
; #define PG8_WAIT_L(n) asm volatile("s_waitcnt lgkmcnt(" #n ")" ::: "memory")
; #define PG8_BAR __builtin_amdgcn_s_barrier()
; #define PG8_SCHED __builtin_amdgcn_sched_barrier(0)
; template <class Epi>
; __device__ __forceinline__ void gemm_phase(PG8_LAS unsigned char* lds, const Gemm g, const StaticOrder& S, const Epi& E) {
;     ...
;       PG8_LDB(B0, 0, 0); PG8_SCHED; PG8_LDA(At, 0, 0); PG8_STAGE(PG8_SA(1, 1), a1 + hstep, voffA);
;       PG8_WAIT_L(8); PG8_BAR; PG8_WAIT_L(0); PG8_MMA(0, 0, At, B0); PG8_BAR; PG8_SCHED;
;       PG8_LDB(B1, 0, 1); PG8_STAGE(PG8_SB(0, 0), b2, voffB);
;       PG8_BAR; PG8_WAIT_L(0); PG8_MMA(0, 1, At, B1); PG8_BAR;
;       PG8_LDA(At, 0, 1); PG8_STAGE(PG8_SA(0, 0), a2, voffA);
;       PG8_BAR; PG8_WAIT_L(0); PG8_MMA(1, 0, At, B0); PG8_BAR; PG8_SCHED;
;       PG8_STAGE(PG8_SB(0, 1), b2 + hstep, voffB);
;       PG8_WAIT_V(6); PG8_BAR; PG8_MMA(1, 1, At, B1); PG8_BAR;
.LBB0_34:
	s_add_u32 s50, s48, 0x100
	s_addc_u32 s51, s49, 0
	s_add_i32 s66, 0, 0x10000
	v_add_u32_e32 v158, s66, v160
	ds_read_b128 v[154:157], v158
	ds_read_b128 v[164:167], v158 offset:1024
	ds_read_b128 v[188:191], v158 offset:2048
	ds_read_b128 v[192:195], v158 offset:3072
	s_cmp_eq_u32 s65, 12
	s_cselect_b32 s55, s11, s51
	s_cselect_b32 s54, s43, s50
	s_cselect_b32 s53, s9, s64
	s_cselect_b32 s52, s47, s63
	v_lshl_add_u64 v[158:159], s[48:49], 0, v[150:151]
	s_add_i32 m0, s56, 0xc000
	ds_read_b128 v[196:199], v162
	ds_read_b128 v[200:203], v162 offset:1024
	ds_read_b128 v[204:207], v162 offset:2048
	ds_read_b128 v[208:211], v162 offset:3072
	ds_read_b128 v[212:215], v162 offset:4096
	ds_read_b128 v[216:219], v162 offset:5120
	ds_read_b128 v[220:223], v162 offset:6144
	ds_read_b128 v[224:227], v162 offset:7168
	global_load_lds_dwordx4 v[158:159], off
	v_lshl_add_u64 v[158:159], s[48:49], 0, v[152:153]
	s_add_i32 m0, s56, 0xe000
	s_nop 0
	global_load_lds_dwordx4 v[158:159], off
	s_waitcnt lgkmcnt(8)
	s_barrier
	s_waitcnt lgkmcnt(0)
	s_setprio 1
	s_waitcnt lgkmcnt(0)
	v_mfma_f32_16x16x32_bf16 v[126:129], v[154:157], v[196:199], v[126:129]
	v_mfma_f32_16x16x32_bf16 v[122:125], v[188:191], v[196:199], v[122:125]
	v_mfma_f32_16x16x32_bf16 v[110:113], v[154:157], v[204:207], v[110:113]
	v_mfma_f32_16x16x32_bf16 v[106:109], v[188:191], v[204:207], v[106:109]
	v_mfma_f32_16x16x32_bf16 v[94:97], v[154:157], v[212:215], v[94:97]
	v_mfma_f32_16x16x32_bf16 v[90:93], v[188:191], v[212:215], v[90:93]
	v_mfma_f32_16x16x32_bf16 v[78:81], v[154:157], v[220:223], v[78:81]
	v_mfma_f32_16x16x32_bf16 v[74:77], v[188:191], v[220:223], v[74:77]
	v_mfma_f32_16x16x32_bf16 v[126:129], v[164:167], v[200:203], v[126:129]
	v_mfma_f32_16x16x32_bf16 v[122:125], v[192:195], v[200:203], v[122:125]
	v_mfma_f32_16x16x32_bf16 v[110:113], v[164:167], v[208:211], v[110:113]
	v_mfma_f32_16x16x32_bf16 v[106:109], v[192:195], v[208:211], v[106:109]
	v_mfma_f32_16x16x32_bf16 v[94:97], v[164:167], v[216:219], v[94:97]
	v_mfma_f32_16x16x32_bf16 v[90:93], v[192:195], v[216:219], v[90:93]
	v_mfma_f32_16x16x32_bf16 v[78:81], v[164:167], v[224:227], v[78:81]
	v_mfma_f32_16x16x32_bf16 v[74:77], v[192:195], v[224:227], v[74:77]
	s_setprio 0
	s_barrier
	s_add_i32 s67, 0, 0x14000
	v_add_u32_e32 v158, s67, v160
	s_add_i32 s48, s66, s28
	ds_read_b128 v[228:231], v158
	ds_read_b128 v[232:235], v158 offset:1024
	ds_read_b128 v[236:239], v158 offset:2048
	ds_read_b128 v[240:243], v158 offset:3072
	v_lshl_add_u64 v[158:159], s[52:53], 0, v[0:1]
	s_mov_b32 m0, s48
	v_lshl_add_u64 v[178:179], s[52:53], 0, v[148:149]
	global_load_lds_dwordx4 v[158:159], off
	s_add_i32 m0, s48, 0x2000
	s_nop 0
	global_load_lds_dwordx4 v[178:179], off
	s_barrier
	s_waitcnt lgkmcnt(0)
	s_setprio 1
	s_waitcnt lgkmcnt(0)
	v_mfma_f32_16x16x32_bf16 v[118:121], v[228:231], v[196:199], v[118:121]
	v_mfma_f32_16x16x32_bf16 v[114:117], v[236:239], v[196:199], v[114:117]
	v_mfma_f32_16x16x32_bf16 v[102:105], v[228:231], v[204:207], v[102:105]
	v_mfma_f32_16x16x32_bf16 v[98:101], v[236:239], v[204:207], v[98:101]
	v_mfma_f32_16x16x32_bf16 v[86:89], v[228:231], v[212:215], v[86:89]
	v_mfma_f32_16x16x32_bf16 v[82:85], v[236:239], v[212:215], v[82:85]
	v_mfma_f32_16x16x32_bf16 v[70:73], v[228:231], v[220:223], v[70:73]
	v_mfma_f32_16x16x32_bf16 v[66:69], v[236:239], v[220:223], v[66:69]
	v_mfma_f32_16x16x32_bf16 v[118:121], v[232:235], v[200:203], v[118:121]
	v_mfma_f32_16x16x32_bf16 v[114:117], v[240:243], v[200:203], v[114:117]
	v_mfma_f32_16x16x32_bf16 v[102:105], v[232:235], v[208:211], v[102:105]
	v_mfma_f32_16x16x32_bf16 v[98:101], v[240:243], v[208:211], v[98:101]
	v_mfma_f32_16x16x32_bf16 v[86:89], v[232:235], v[216:219], v[86:89]
	v_mfma_f32_16x16x32_bf16 v[82:85], v[240:243], v[216:219], v[82:85]
	v_mfma_f32_16x16x32_bf16 v[70:73], v[232:235], v[224:227], v[70:73]
	v_mfma_f32_16x16x32_bf16 v[66:69], v[240:243], v[224:227], v[66:69]
	s_setprio 0
	s_mov_b32 m0, s56
	v_lshl_add_u64 v[244:245], s[54:55], 0, v[0:1]
	s_barrier
	ds_read_b128 v[196:199], v162 offset:16384
	ds_read_b128 v[200:203], v162 offset:17408
	ds_read_b128 v[204:207], v162 offset:18432
	ds_read_b128 v[208:211], v162 offset:19456
	ds_read_b128 v[212:215], v162 offset:20480
	ds_read_b128 v[216:219], v162 offset:21504
	ds_read_b128 v[220:223], v162 offset:22528
	ds_read_b128 v[224:227], v162 offset:23552
	global_load_lds_dwordx4 v[244:245], off
	v_lshl_add_u64 v[246:247], s[54:55], 0, v[148:149]
	s_mov_b32 m0, s57
	s_nop 0
	global_load_lds_dwordx4 v[246:247], off
	s_barrier
	s_waitcnt lgkmcnt(0)
	s_setprio 1
	s_waitcnt lgkmcnt(0)
	v_mfma_f32_16x16x32_bf16 v[62:65], v[154:157], v[196:199], v[62:65]
	v_mfma_f32_16x16x32_bf16 v[58:61], v[188:191], v[196:199], v[58:61]
	v_mfma_f32_16x16x32_bf16 v[46:49], v[154:157], v[204:207], v[46:49]
	v_mfma_f32_16x16x32_bf16 v[42:45], v[188:191], v[204:207], v[42:45]
	v_mfma_f32_16x16x32_bf16 v[30:33], v[154:157], v[212:215], v[30:33]
	v_mfma_f32_16x16x32_bf16 v[26:29], v[188:191], v[212:215], v[26:29]
	v_mfma_f32_16x16x32_bf16 v[14:17], v[154:157], v[220:223], v[14:17]
	v_mfma_f32_16x16x32_bf16 v[10:13], v[188:191], v[220:223], v[10:13]
	v_mfma_f32_16x16x32_bf16 v[62:65], v[164:167], v[200:203], v[62:65]
	v_mfma_f32_16x16x32_bf16 v[58:61], v[192:195], v[200:203], v[58:61]
	v_mfma_f32_16x16x32_bf16 v[46:49], v[164:167], v[208:211], v[46:49]
	v_mfma_f32_16x16x32_bf16 v[42:45], v[192:195], v[208:211], v[42:45]
	v_mfma_f32_16x16x32_bf16 v[30:33], v[164:167], v[216:219], v[30:33]
	v_mfma_f32_16x16x32_bf16 v[26:29], v[192:195], v[216:219], v[26:29]
	v_mfma_f32_16x16x32_bf16 v[14:17], v[164:167], v[224:227], v[14:17]
	v_mfma_f32_16x16x32_bf16 v[10:13], v[192:195], v[224:227], v[10:13]
	s_setprio 0
	s_barrier
; #define PG8_STAGE(bufoff, gbase, voff) do { _Pragma("unroll") for (int _i = 0; _i < 2; ++_i) \
;     __builtin_amdgcn_global_load_lds((const unsigned*)((const char*)(gbase) + (voff)[_i]), (PG8_LAS unsigned*)(lds + (bufoff) + ldsw + _i * 8192), 16, 0, 0); } while (0)
; #define PG8_LDA(dst, b, h) do { _Pragma("unroll") for (int m = 0; m < 4; ++m) _Pragma("unroll") for (int k = 0; k < 2; ++k) dst[m][k] = *(const PG8_LAS bf16x8*)(lds + PG8_SA(b, h) + aoff + m * 2048 + k * 1024); } while (0)
; #define PG8_LDB(dst, b, h) do { _Pragma("unroll") for (int n = 0; n < 2; ++n) _Pragma("unroll") for (int k = 0; k < 2; ++k) dst[n][k] = *(const PG8_LAS bf16x8*)(lds + PG8_SB(b, h) + boff + n * 2048 + k * 1024); } while (0)
; #define PG8_MMA(ai, bj, At, Bt) do { __builtin_amdgcn_s_setprio(1); _Pragma("unroll") for (int m = 0; m < 4; ++m) _Pragma("unroll") for (int n = 0; n < 2; ++n) _Pragma("unroll") for (int k = 0; k < 2; ++k) \
;     acc[ai][bj][m][n] = __builtin_amdgcn_mfma_f32_16x16x32_bf16(Bt[n][k], At[m][k], acc[ai][bj][m][n], 0, 0, 0); __builtin_amdgcn_s_setprio(0); } while (0)
; #define PG8_WAIT_V(n) asm volatile("s_waitcnt vmcnt(" #n ")" ::: "memory")
; #define PG8_WAIT_L(n) asm volatile("s_waitcnt lgkmcnt(" #n ")" ::: "memory")
; #define PG8_BAR __builtin_amdgcn_s_barrier()
; #define PG8_SCHED __builtin_amdgcn_sched_barrier(0)
; template <class Epi>
; __device__ __forceinline__ void gemm_phase(PG8_LAS unsigned char* lds, const Gemm g, const StaticOrder& S, const Epi& E) {
;     ...
;       PG8_WAIT_V(6); PG8_BAR; PG8_MMA(1, 1, At, B1); PG8_BAR;
;       PG8_LDB(B0, 1, 0); PG8_SCHED; PG8_LDA(At, 1, 0); PG8_STAGE(PG8_SA(0, 1), a2 + hstep, voffA);
;       PG8_WAIT_L(8); PG8_BAR; PG8_WAIT_L(0); PG8_MMA(0, 0, At, B0); PG8_BAR; PG8_SCHED;
;       PG8_LDB(B1, 1, 1); PG8_STAGE(PG8_SB(1, 0), b3, voffB);
;       PG8_BAR; PG8_WAIT_L(0); PG8_MMA(0, 1, At, B1); PG8_BAR;
;       PG8_LDA(At, 1, 1); PG8_STAGE(PG8_SA(1, 0), a3, voffA);
;       PG8_BAR; PG8_WAIT_L(0); PG8_MMA(1, 0, At, B0); PG8_BAR; PG8_SCHED;
	s_add_u32 s48, s52, 0x40000
	s_addc_u32 s49, s53, 0
	s_add_i32 s66, s67, s28
	v_lshl_add_u64 v[154:155], s[48:49], 0, v[0:1]
	s_mov_b32 m0, s66
	s_nop 0
	global_load_lds_dwordx4 v[154:155], off
	v_lshl_add_u64 v[154:155], s[48:49], 0, v[148:149]
	s_add_i32 m0, s66, 0x2000
	s_nop 0
	global_load_lds_dwordx4 v[154:155], off
	s_waitcnt vmcnt(6)
	s_barrier
	s_setprio 1
	v_mfma_f32_16x16x32_bf16 v[54:57], v[228:231], v[196:199], v[54:57]
	v_mfma_f32_16x16x32_bf16 v[50:53], v[236:239], v[196:199], v[50:53]
	v_mfma_f32_16x16x32_bf16 v[38:41], v[228:231], v[204:207], v[38:41]
	v_mfma_f32_16x16x32_bf16 v[34:37], v[236:239], v[204:207], v[34:37]
	v_mfma_f32_16x16x32_bf16 v[22:25], v[228:231], v[212:215], v[22:25]
	v_mfma_f32_16x16x32_bf16 v[18:21], v[236:239], v[212:215], v[18:21]
	v_mfma_f32_16x16x32_bf16 v[6:9], v[228:231], v[220:223], v[6:9]
	v_mfma_f32_16x16x32_bf16 v[2:5], v[236:239], v[220:223], v[2:5]
	v_mfma_f32_16x16x32_bf16 v[54:57], v[232:235], v[200:203], v[54:57]
	v_mfma_f32_16x16x32_bf16 v[50:53], v[240:243], v[200:203], v[50:53]
	v_mfma_f32_16x16x32_bf16 v[38:41], v[232:235], v[208:211], v[38:41]
	v_mfma_f32_16x16x32_bf16 v[34:37], v[240:243], v[208:211], v[34:37]
	v_mfma_f32_16x16x32_bf16 v[22:25], v[232:235], v[216:219], v[22:25]
	v_mfma_f32_16x16x32_bf16 v[18:21], v[240:243], v[216:219], v[18:21]
	v_mfma_f32_16x16x32_bf16 v[6:9], v[232:235], v[224:227], v[6:9]
	v_mfma_f32_16x16x32_bf16 v[2:5], v[240:243], v[224:227], v[2:5]
	s_setprio 0
	s_add_i32 s66, 0, 0x18000
	v_add_u32_e32 v163, s66, v160
	s_barrier
	ds_read_b128 v[154:157], v163
	ds_read_b128 v[164:167], v163 offset:1024
	ds_read_b128 v[188:191], v163 offset:2048
	ds_read_b128 v[192:195], v163 offset:3072
	s_add_u32 s48, s54, 0x40000
	s_addc_u32 s49, s55, 0
	s_mov_b32 m0, s58
	v_lshl_add_u64 v[228:229], s[48:49], 0, v[0:1]
	ds_read_b128 v[196:199], v162 offset:32768
	ds_read_b128 v[200:203], v162 offset:33792
	ds_read_b128 v[204:207], v162 offset:34816
	ds_read_b128 v[208:211], v162 offset:35840
	ds_read_b128 v[212:215], v162 offset:36864
	ds_read_b128 v[216:219], v162 offset:37888
	ds_read_b128 v[220:223], v162 offset:38912
	ds_read_b128 v[224:227], v162 offset:39936
	global_load_lds_dwordx4 v[228:229], off
	v_lshl_add_u64 v[228:229], s[48:49], 0, v[148:149]
	s_mov_b32 m0, s59
	s_nop 0
	global_load_lds_dwordx4 v[228:229], off
	s_waitcnt lgkmcnt(8)
	s_barrier
	s_waitcnt lgkmcnt(0)
	s_setprio 1
	s_waitcnt lgkmcnt(0)
	v_mfma_f32_16x16x32_bf16 v[126:129], v[154:157], v[196:199], v[126:129]
	v_mfma_f32_16x16x32_bf16 v[122:125], v[188:191], v[196:199], v[122:125]
	v_mfma_f32_16x16x32_bf16 v[110:113], v[154:157], v[204:207], v[110:113]
	v_mfma_f32_16x16x32_bf16 v[106:109], v[188:191], v[204:207], v[106:109]
	v_mfma_f32_16x16x32_bf16 v[94:97], v[154:157], v[212:215], v[94:97]
	v_mfma_f32_16x16x32_bf16 v[90:93], v[188:191], v[212:215], v[90:93]
	v_mfma_f32_16x16x32_bf16 v[78:81], v[154:157], v[220:223], v[78:81]
	v_mfma_f32_16x16x32_bf16 v[74:77], v[188:191], v[220:223], v[74:77]
	v_mfma_f32_16x16x32_bf16 v[126:129], v[164:167], v[200:203], v[126:129]
	v_mfma_f32_16x16x32_bf16 v[122:125], v[192:195], v[200:203], v[122:125]
	v_mfma_f32_16x16x32_bf16 v[110:113], v[164:167], v[208:211], v[110:113]
	v_mfma_f32_16x16x32_bf16 v[106:109], v[192:195], v[208:211], v[106:109]
	v_mfma_f32_16x16x32_bf16 v[94:97], v[164:167], v[216:219], v[94:97]
	v_mfma_f32_16x16x32_bf16 v[90:93], v[192:195], v[216:219], v[90:93]
	v_mfma_f32_16x16x32_bf16 v[78:81], v[164:167], v[224:227], v[78:81]
	v_mfma_f32_16x16x32_bf16 v[74:77], v[192:195], v[224:227], v[74:77]
	s_setprio 0
	s_barrier
	s_add_i32 s54, 0, 0x1c000
	s_add_i32 s48, s66, s28
	v_add_u32_e32 v163, s54, v160
	v_lshl_add_u64 v[158:159], v[158:159], 0, s[4:5]
	s_mov_b32 m0, s48
	ds_read_b128 v[228:231], v163
	ds_read_b128 v[232:235], v163 offset:1024
	ds_read_b128 v[236:239], v163 offset:2048
	ds_read_b128 v[240:243], v163 offset:3072
	global_load_lds_dwordx4 v[158:159], off
	v_lshl_add_u64 v[158:159], v[178:179], 0, s[4:5]
	s_add_i32 m0, s48, 0x2000
	s_nop 0
	global_load_lds_dwordx4 v[158:159], off
	s_barrier
	s_waitcnt lgkmcnt(0)
	s_setprio 1
	s_waitcnt lgkmcnt(0)
	v_mfma_f32_16x16x32_bf16 v[118:121], v[228:231], v[196:199], v[118:121]
	v_mfma_f32_16x16x32_bf16 v[114:117], v[236:239], v[196:199], v[114:117]
	v_mfma_f32_16x16x32_bf16 v[102:105], v[228:231], v[204:207], v[102:105]
	v_mfma_f32_16x16x32_bf16 v[98:101], v[236:239], v[204:207], v[98:101]
	v_mfma_f32_16x16x32_bf16 v[86:89], v[228:231], v[212:215], v[86:89]
	v_mfma_f32_16x16x32_bf16 v[82:85], v[236:239], v[212:215], v[82:85]
	v_mfma_f32_16x16x32_bf16 v[70:73], v[228:231], v[220:223], v[70:73]
	v_mfma_f32_16x16x32_bf16 v[66:69], v[236:239], v[220:223], v[66:69]
	v_mfma_f32_16x16x32_bf16 v[118:121], v[232:235], v[200:203], v[118:121]
	v_mfma_f32_16x16x32_bf16 v[114:117], v[240:243], v[200:203], v[114:117]
	v_mfma_f32_16x16x32_bf16 v[102:105], v[232:235], v[208:211], v[102:105]
	v_mfma_f32_16x16x32_bf16 v[98:101], v[240:243], v[208:211], v[98:101]
	v_mfma_f32_16x16x32_bf16 v[86:89], v[232:235], v[216:219], v[86:89]
	v_mfma_f32_16x16x32_bf16 v[82:85], v[240:243], v[216:219], v[82:85]
	v_mfma_f32_16x16x32_bf16 v[70:73], v[232:235], v[224:227], v[70:73]
	v_mfma_f32_16x16x32_bf16 v[66:69], v[240:243], v[224:227], v[66:69]
	s_setprio 0
	s_mov_b32 m0, s60
	v_lshl_add_u64 v[158:159], v[244:245], 0, s[4:5]
	s_barrier
	ds_read_b128 v[196:199], v162 offset:49152
	ds_read_b128 v[200:203], v162 offset:50176
	ds_read_b128 v[204:207], v162 offset:51200
	ds_read_b128 v[208:211], v162 offset:52224
	ds_read_b128 v[212:215], v162 offset:53248
	ds_read_b128 v[216:219], v162 offset:54272
	ds_read_b128 v[220:223], v162 offset:55296
	ds_read_b128 v[224:227], v162 offset:56320
	global_load_lds_dwordx4 v[158:159], off
	v_lshl_add_u64 v[158:159], v[246:247], 0, s[4:5]
	s_mov_b32 m0, s61
	s_nop 0
	global_load_lds_dwordx4 v[158:159], off
	s_barrier
; #define PG8_STAGE(bufoff, gbase, voff) do { _Pragma("unroll") for (int _i = 0; _i < 2; ++_i) \
;     __builtin_amdgcn_global_load_lds((const unsigned*)((const char*)(gbase) + (voff)[_i]), (PG8_LAS unsigned*)(lds + (bufoff) + ldsw + _i * 8192), 16, 0, 0); } while (0)
; #define PG8_MMA(ai, bj, At, Bt) do { __builtin_amdgcn_s_setprio(1); _Pragma("unroll") for (int m = 0; m < 4; ++m) _Pragma("unroll") for (int n = 0; n < 2; ++n) _Pragma("unroll") for (int k = 0; k < 2; ++k) \
;     acc[ai][bj][m][n] = __builtin_amdgcn_mfma_f32_16x16x32_bf16(Bt[n][k], At[m][k], acc[ai][bj][m][n], 0, 0, 0); __builtin_amdgcn_s_setprio(0); } while (0)
; #define PG8_WAIT_V(n) asm volatile("s_waitcnt vmcnt(" #n ")" ::: "memory")
; #define PG8_WAIT_L(n) asm volatile("s_waitcnt lgkmcnt(" #n ")" ::: "memory")
; #define PG8_BAR __builtin_amdgcn_s_barrier()
; #define PG8_SCHED __builtin_amdgcn_sched_barrier(0)
; template <class Epi>
; __device__ __forceinline__ void gemm_phase(PG8_LAS unsigned char* lds, const Gemm g, const StaticOrder& S, const Epi& E) {
;     ...
;       PG8_BAR; PG8_WAIT_L(0); PG8_MMA(1, 0, At, B0); PG8_BAR; PG8_SCHED;
;       PG8_STAGE(PG8_SB(1, 1), b3 + hstep, voffB);
;       PG8_WAIT_V(6); PG8_BAR; PG8_MMA(1, 1, At, B1); PG8_BAR;
	s_waitcnt lgkmcnt(0)
	s_setprio 1
	s_waitcnt lgkmcnt(0)
	v_mfma_f32_16x16x32_bf16 v[62:65], v[154:157], v[196:199], v[62:65]
	v_mfma_f32_16x16x32_bf16 v[58:61], v[188:191], v[196:199], v[58:61]
	v_mfma_f32_16x16x32_bf16 v[46:49], v[154:157], v[204:207], v[46:49]
	v_mfma_f32_16x16x32_bf16 v[42:45], v[188:191], v[204:207], v[42:45]
	v_mfma_f32_16x16x32_bf16 v[30:33], v[154:157], v[212:215], v[30:33]
	v_mfma_f32_16x16x32_bf16 v[26:29], v[188:191], v[212:215], v[26:29]
	v_mfma_f32_16x16x32_bf16 v[14:17], v[154:157], v[220:223], v[14:17]
	v_mfma_f32_16x16x32_bf16 v[10:13], v[188:191], v[220:223], v[10:13]
	v_mfma_f32_16x16x32_bf16 v[62:65], v[164:167], v[200:203], v[62:65]
	v_mfma_f32_16x16x32_bf16 v[58:61], v[192:195], v[200:203], v[58:61]
	v_mfma_f32_16x16x32_bf16 v[46:49], v[164:167], v[208:211], v[46:49]
	v_mfma_f32_16x16x32_bf16 v[42:45], v[192:195], v[208:211], v[42:45]
	v_mfma_f32_16x16x32_bf16 v[30:33], v[164:167], v[216:219], v[30:33]
	v_mfma_f32_16x16x32_bf16 v[26:29], v[192:195], v[216:219], v[26:29]
	v_mfma_f32_16x16x32_bf16 v[14:17], v[164:167], v[224:227], v[14:17]
	v_mfma_f32_16x16x32_bf16 v[10:13], v[192:195], v[224:227], v[10:13]
	s_setprio 0
	s_barrier
	s_add_u32 s48, s52, 0x40080
	s_addc_u32 s49, s53, 0
	s_add_i32 s52, s54, s28
	v_lshl_add_u64 v[154:155], s[48:49], 0, v[0:1]
	s_mov_b32 m0, s52
	s_nop 0
	global_load_lds_dwordx4 v[154:155], off
	v_lshl_add_u64 v[154:155], s[48:49], 0, v[148:149]
	s_add_i32 m0, s52, 0x2000
	s_nop 0
	global_load_lds_dwordx4 v[154:155], off
	s_waitcnt vmcnt(6)
	s_barrier
	s_setprio 1
	v_mfma_f32_16x16x32_bf16 v[54:57], v[228:231], v[196:199], v[54:57]
	v_mfma_f32_16x16x32_bf16 v[50:53], v[236:239], v[196:199], v[50:53]
	v_mfma_f32_16x16x32_bf16 v[38:41], v[228:231], v[204:207], v[38:41]
	v_mfma_f32_16x16x32_bf16 v[34:37], v[236:239], v[204:207], v[34:37]
	v_mfma_f32_16x16x32_bf16 v[22:25], v[228:231], v[212:215], v[22:25]
	v_mfma_f32_16x16x32_bf16 v[18:21], v[236:239], v[212:215], v[18:21]
	v_mfma_f32_16x16x32_bf16 v[6:9], v[228:231], v[220:223], v[6:9]
	v_mfma_f32_16x16x32_bf16 v[2:5], v[236:239], v[220:223], v[2:5]
	v_mfma_f32_16x16x32_bf16 v[54:57], v[232:235], v[200:203], v[54:57]
	v_mfma_f32_16x16x32_bf16 v[50:53], v[240:243], v[200:203], v[50:53]
	v_mfma_f32_16x16x32_bf16 v[38:41], v[232:235], v[208:211], v[38:41]
	v_mfma_f32_16x16x32_bf16 v[34:37], v[240:243], v[208:211], v[34:37]
	v_mfma_f32_16x16x32_bf16 v[22:25], v[232:235], v[216:219], v[22:25]
	v_mfma_f32_16x16x32_bf16 v[18:21], v[240:243], v[216:219], v[18:21]
	v_mfma_f32_16x16x32_bf16 v[6:9], v[232:235], v[224:227], v[6:9]
	v_mfma_f32_16x16x32_bf16 v[2:5], v[240:243], v[224:227], v[2:5]
	s_setprio 0
	s_add_i32 s65, s65, 2
	s_add_u32 s63, s63, 0x100
	s_addc_u32 s64, s64, 0
	s_cmp_gt_u32 s65, 13
	s_mov_b64 s[48:49], s[50:51]
	s_barrier
	s_cbranch_scc0 .LBB0_34
	v_readlane_b32 s80, v254, 5
	v_readlane_b32 s81, v254, 6
	v_readlane_b32 s82, v254, 7
	v_readlane_b32 s83, v254, 8
	s_cmp_ge_i32 s46, 65
	s_cselect_b32 s68, 1, 0
	s_mul_i32 s69, s68, 65
	s_sub_i32 s69, s46, s69
	s_cmp_eq_u32 s69, 0
	s_cbranch_scc1 .LepiA_ctx
	s_add_i32 s69, s69, -1
	s_lshl_b32 s69, s69, 8
	s_lshl_b32 s70, s68, 14
	s_add_i32 s69, s69, s70
	s_lshl_b32 s69, s69, 12
	s_add_u32 s70, s80, s69
	s_addc_u32 s71, s81, 0
	s_mul_i32 s68, s68, 0x3000
	s_branch .LepiA_go
.LepiA_ctx:
	s_and_b64 vcc, exec, s[12:13]
	s_cbranch_vccnz .LepiA_done
	s_lshl_b32 s69, s68, 20
	s_add_u32 s70, s82, s69
	s_addc_u32 s71, s83, 0
	s_movk_i32 s68, 0x6000
.LepiA_go:
	s_add_u32 s72, s6, s68
	s_addc_u32 s73, s7, 0
	s_add_u32 s72, s72, 0x2000
	s_addc_u32 s73, s73, 0
	v_lshl_or_b32 v154, s42, 8, v161
	v_lshlrev_b32_e32 v154, 2, v154
	v_mov_b32_e32 v155, 0
	v_lshl_add_u64 v[166:167], v[154:155], 0, s[72:73]
	global_load_dwordx4 v[228:231], v[166:167], off
	global_load_dwordx4 v[232:235], v[166:167], off offset:64
	global_load_dwordx4 v[236:239], v[166:167], off offset:512
	global_load_dwordx4 v[240:243], v[166:167], off offset:576
	v_lshl_add_u32 v154, v147, 12, v154
	v_lshl_add_u64 v[220:221], v[154:155], 0, s[70:71]
	v_mov_b64_e32 v[156:157], v[220:221]
	global_load_dwordx4 v[188:191], v[156:157], off
	global_load_dwordx4 v[192:195], v[156:157], off offset:64
	global_load_dwordx4 v[196:199], v[156:157], off offset:512
	global_load_dwordx4 v[200:203], v[156:157], off offset:576
	v_add_co_u32_e32 v158, vcc, 0x10000, v220
	s_nop 1
	v_addc_co_u32_e32 v159, vcc, 0, v221, vcc
	global_load_dwordx4 v[204:207], v[158:159], off
	global_load_dwordx4 v[208:211], v[158:159], off offset:64
	global_load_dwordx4 v[212:215], v[158:159], off offset:512
	global_load_dwordx4 v[216:219], v[158:159], off offset:576
	s_waitcnt vmcnt(4)
	v_pk_fma_f32 v[126:127], v[126:127], v[228:229], v[188:189]
	v_pk_fma_f32 v[128:129], v[128:129], v[230:231], v[190:191]
	v_pk_fma_f32 v[122:123], v[122:123], v[232:233], v[192:193]
	v_pk_fma_f32 v[124:125], v[124:125], v[234:235], v[194:195]
	v_pk_fma_f32 v[118:119], v[118:119], v[236:237], v[196:197]
	v_pk_fma_f32 v[120:121], v[120:121], v[238:239], v[198:199]
	v_pk_fma_f32 v[114:115], v[114:115], v[240:241], v[200:201]
	v_pk_fma_f32 v[116:117], v[116:117], v[242:243], v[202:203]
	global_store_dwordx4 v[156:157], v[126:129], off
	global_store_dwordx4 v[156:157], v[122:125], off offset:64
	global_store_dwordx4 v[156:157], v[118:121], off offset:512
	global_store_dwordx4 v[156:157], v[114:117], off offset:576
	v_add_co_u32_e32 v156, vcc, 0x20000, v220
	s_nop 1
	v_addc_co_u32_e32 v157, vcc, 0, v221, vcc
	global_load_dwordx4 v[126:129], v[156:157], off
	global_load_dwordx4 v[122:125], v[156:157], off offset:64
	global_load_dwordx4 v[118:121], v[156:157], off offset:512
	global_load_dwordx4 v[114:117], v[156:157], off offset:576
	s_waitcnt vmcnt(8)
;   __device__ __forceinline__ void operator()(const f32x4 (&acc)[2][2][4][2], const pg8::Unit& u, int wr, int wc, int fr, int fq) const {
;     ...
;       for (int m = 0; m < 4; ++m) { const int row = u.pm * 256 + ai * 128 + wr * 64 + m * 16 + fr;
; #pragma unroll
;         for (int bj = 0; bj < 2; ++bj)
; #pragma unroll
;           for (int n = 0; n < 2; ++n) f(row, u.pn * 256 + bj * 128 + wc * 32 + n * 16 + 4 * fq, acc[ai][bj][m][n]); }
	v_pk_fma_f32 v[110:111], v[110:111], v[228:229], v[204:205]
	v_pk_fma_f32 v[112:113], v[112:113], v[230:231], v[206:207]
	v_pk_fma_f32 v[106:107], v[106:107], v[232:233], v[208:209]
	v_pk_fma_f32 v[108:109], v[108:109], v[234:235], v[210:211]
	v_pk_fma_f32 v[102:103], v[102:103], v[236:237], v[212:213]
	v_pk_fma_f32 v[104:105], v[104:105], v[238:239], v[214:215]
	v_pk_fma_f32 v[98:99], v[98:99], v[240:241], v[216:217]
	v_pk_fma_f32 v[100:101], v[100:101], v[242:243], v[218:219]
	global_store_dwordx4 v[158:159], v[110:113], off
	global_store_dwordx4 v[158:159], v[106:109], off offset:64
	global_store_dwordx4 v[158:159], v[102:105], off offset:512
	global_store_dwordx4 v[158:159], v[98:101], off offset:576
	v_add_co_u32_e32 v158, vcc, 0x30000, v220
	s_nop 1
	v_addc_co_u32_e32 v159, vcc, 0, v221, vcc
	global_load_dwordx4 v[110:113], v[158:159], off
	global_load_dwordx4 v[106:109], v[158:159], off offset:64
	global_load_dwordx4 v[102:105], v[158:159], off offset:512
	global_load_dwordx4 v[98:101], v[158:159], off offset:576
	s_waitcnt vmcnt(8)
	v_pk_fma_f32 v[94:95], v[94:95], v[228:229], v[126:127]
	v_pk_fma_f32 v[96:97], v[96:97], v[230:231], v[128:129]
	v_pk_fma_f32 v[90:91], v[90:91], v[232:233], v[122:123]
	v_pk_fma_f32 v[92:93], v[92:93], v[234:235], v[124:125]
	v_pk_fma_f32 v[86:87], v[86:87], v[236:237], v[118:119]
	v_pk_fma_f32 v[88:89], v[88:89], v[238:239], v[120:121]
	v_pk_fma_f32 v[82:83], v[82:83], v[240:241], v[114:115]
	v_pk_fma_f32 v[84:85], v[84:85], v[242:243], v[116:117]
	global_store_dwordx4 v[156:157], v[94:97], off
	global_store_dwordx4 v[156:157], v[90:93], off offset:64
	global_store_dwordx4 v[156:157], v[86:89], off offset:512
	global_store_dwordx4 v[156:157], v[82:85], off offset:576
	v_add_co_u32_e32 v156, vcc, 0x80000, v220
	s_nop 1
	v_addc_co_u32_e32 v157, vcc, 0, v221, vcc
	global_load_dwordx4 v[94:97], v[156:157], off
	global_load_dwordx4 v[90:93], v[156:157], off offset:64
	global_load_dwordx4 v[86:89], v[156:157], off offset:512
	global_load_dwordx4 v[82:85], v[156:157], off offset:576
	s_waitcnt vmcnt(8)
	v_pk_fma_f32 v[78:79], v[78:79], v[228:229], v[110:111]
	v_pk_fma_f32 v[80:81], v[80:81], v[230:231], v[112:113]
	v_pk_fma_f32 v[74:75], v[74:75], v[232:233], v[106:107]
	v_pk_fma_f32 v[76:77], v[76:77], v[234:235], v[108:109]
	v_pk_fma_f32 v[70:71], v[70:71], v[236:237], v[102:103]
	v_pk_fma_f32 v[72:73], v[72:73], v[238:239], v[104:105]
	v_pk_fma_f32 v[66:67], v[66:67], v[240:241], v[98:99]
	v_pk_fma_f32 v[68:69], v[68:69], v[242:243], v[100:101]
	global_store_dwordx4 v[158:159], v[78:81], off
	global_store_dwordx4 v[158:159], v[74:77], off offset:64
	global_store_dwordx4 v[158:159], v[70:73], off offset:512
	global_store_dwordx4 v[158:159], v[66:69], off offset:576
	v_add_co_u32_e32 v158, vcc, 0x90000, v220
	s_nop 1
	v_addc_co_u32_e32 v159, vcc, 0, v221, vcc
	global_load_dwordx4 v[78:81], v[158:159], off
	global_load_dwordx4 v[74:77], v[158:159], off offset:64
	global_load_dwordx4 v[70:73], v[158:159], off offset:512
	global_load_dwordx4 v[66:69], v[158:159], off offset:576
	s_waitcnt vmcnt(8)
	v_pk_fma_f32 v[62:63], v[62:63], v[228:229], v[94:95]
	v_pk_fma_f32 v[64:65], v[64:65], v[230:231], v[96:97]
	v_pk_fma_f32 v[58:59], v[58:59], v[232:233], v[90:91]
	v_pk_fma_f32 v[60:61], v[60:61], v[234:235], v[92:93]
	v_pk_fma_f32 v[54:55], v[54:55], v[236:237], v[86:87]
	v_pk_fma_f32 v[56:57], v[56:57], v[238:239], v[88:89]
	v_pk_fma_f32 v[50:51], v[50:51], v[240:241], v[82:83]
	v_pk_fma_f32 v[52:53], v[52:53], v[242:243], v[84:85]
	global_store_dwordx4 v[156:157], v[62:65], off
	global_store_dwordx4 v[156:157], v[58:61], off offset:64
	global_store_dwordx4 v[156:157], v[54:57], off offset:512
	global_store_dwordx4 v[156:157], v[50:53], off offset:576
	v_add_co_u32_e32 v156, vcc, 0xa0000, v220
	s_nop 1
	v_addc_co_u32_e32 v157, vcc, 0, v221, vcc
	global_load_dwordx4 v[62:65], v[156:157], off
	global_load_dwordx4 v[58:61], v[156:157], off offset:64
	global_load_dwordx4 v[54:57], v[156:157], off offset:512
	global_load_dwordx4 v[50:53], v[156:157], off offset:576
	s_waitcnt vmcnt(8)
	v_pk_fma_f32 v[46:47], v[46:47], v[228:229], v[78:79]
	v_pk_fma_f32 v[48:49], v[48:49], v[230:231], v[80:81]
	v_pk_fma_f32 v[42:43], v[42:43], v[232:233], v[74:75]
	v_pk_fma_f32 v[44:45], v[44:45], v[234:235], v[76:77]
	v_pk_fma_f32 v[38:39], v[38:39], v[236:237], v[70:71]
	v_pk_fma_f32 v[40:41], v[40:41], v[238:239], v[72:73]
	v_pk_fma_f32 v[34:35], v[34:35], v[240:241], v[66:67]
	v_pk_fma_f32 v[36:37], v[36:37], v[242:243], v[68:69]
	global_store_dwordx4 v[158:159], v[46:49], off
	global_store_dwordx4 v[158:159], v[42:45], off offset:64
	global_store_dwordx4 v[158:159], v[38:41], off offset:512
	global_store_dwordx4 v[158:159], v[34:37], off offset:576
	v_add_co_u32_e32 v158, vcc, 0xb0000, v220
	s_nop 1
	v_addc_co_u32_e32 v159, vcc, 0, v221, vcc
	global_load_dwordx4 v[46:49], v[158:159], off
	global_load_dwordx4 v[42:45], v[158:159], off offset:64
	global_load_dwordx4 v[38:41], v[158:159], off offset:512
	global_load_dwordx4 v[34:37], v[158:159], off offset:576
	s_waitcnt vmcnt(8)
	v_pk_fma_f32 v[30:31], v[30:31], v[228:229], v[62:63]
	v_pk_fma_f32 v[32:33], v[32:33], v[230:231], v[64:65]
	v_pk_fma_f32 v[26:27], v[26:27], v[232:233], v[58:59]
	v_pk_fma_f32 v[28:29], v[28:29], v[234:235], v[60:61]
	v_pk_fma_f32 v[22:23], v[22:23], v[236:237], v[54:55]
	v_pk_fma_f32 v[24:25], v[24:25], v[238:239], v[56:57]
	v_pk_fma_f32 v[18:19], v[18:19], v[240:241], v[50:51]
	v_pk_fma_f32 v[20:21], v[20:21], v[242:243], v[52:53]
	global_store_dwordx4 v[156:157], v[30:33], off
	global_store_dwordx4 v[156:157], v[26:29], off offset:64
	global_store_dwordx4 v[156:157], v[22:25], off offset:512
	global_store_dwordx4 v[156:157], v[18:21], off offset:576
	s_waitcnt vmcnt(4)
	v_pk_fma_f32 v[14:15], v[14:15], v[228:229], v[46:47]
	v_pk_fma_f32 v[16:17], v[16:17], v[230:231], v[48:49]
	v_pk_fma_f32 v[10:11], v[10:11], v[232:233], v[42:43]
	v_pk_fma_f32 v[12:13], v[12:13], v[234:235], v[44:45]
	v_pk_fma_f32 v[6:7], v[6:7], v[236:237], v[38:39]
	v_pk_fma_f32 v[8:9], v[8:9], v[238:239], v[40:41]
	v_pk_fma_f32 v[2:3], v[2:3], v[240:241], v[34:35]
	v_pk_fma_f32 v[4:5], v[4:5], v[242:243], v[36:37]
	global_store_dwordx4 v[158:159], v[14:17], off
	global_store_dwordx4 v[158:159], v[10:13], off offset:64
	global_store_dwordx4 v[158:159], v[6:9], off offset:512
	global_store_dwordx4 v[158:159], v[2:5], off offset:576
.LepiA_done:
	v_readlane_b32 s64, v254, 56
	s_movk_i32 s65, 0x100
	s_mov_b64 s[42:43], exec
	s_branch .LBB0_30

; __device__ __forceinline__ void ph_r7_ca(const P& p, int j, int win, char* smem) {
;     ...
;     {
;       const int rowA = rowmap(d, b, 64 * c + 16 * ti + l15);
;       const float* w0 = p.r7_w0 + (size_t)(j * 2 + d) * 1024 + h * 64; const float* a0 = p.r7_a0 + (size_t)(j * 2 + d) * 1024 + h * 64;
; #pragma unroll
;       for (int tt = 0; tt < 2; tt++) { const int tj = tj0 + tt; f32x4 aw = f32x4{0.f, 0.f, 0.f, 0.f}, aa = aw;
; #pragma unroll
;         for (int ks = 0; ks < 2; ks++) {
;           bf16x8 xw = *(const bf16x8*)(WMb + (size_t)rowA * 128 + d * 64 + 32 * ks + 8 * q4), xa = *(const bf16x8*)(AMb + (size_t)rowA * 128 + d * 64 + 32 * ks + 8 * q4);
;           bf16x8 yw = *(const bf16x8*)(p.W + WR_UP + d * 65536 + (size_t)(h * 64 + 16 * tj + l15) * 64 + 32 * ks + 8 * q4);
;           bf16x8 ya = *(const bf16x8*)(p.W + WR_UP + (2 + d) * 65536 + (size_t)(h * 64 + 16 * tj + l15) * 64 + 32 * ks + 8 * q4);
;           aw = __builtin_amdgcn_mfma_f32_16x16x32_bf16(xw, yw, aw, 0, 0, 0); aa = __builtin_amdgcn_mfma_f32_16x16x32_bf16(xa, ya, aa, 0, 0, 0); }
;         const int ch = 16 * tj + l15; const float w0v = w0[ch], a0v = a0[ch];
.LBB0_187:
	s_mul_hi_i32 s28, s84, 0x66666667
	s_lshr_b32 s30, s28, 31
	s_ashr_i32 s28, s28, 3
	s_add_i32 s28, s28, s30
	s_sub_i32 s30, s18, s28
	s_mul_i32 s30, s30, 20
	s_add_i32 s30, s30, s84
	s_and_b32 s86, s28, 1
	s_lshr_b32 s90, s28, 5
	s_bfe_u32 s85, s28, 0x40001
	s_lshl_b32 s87, s30, 6
	s_cmp_eq_u32 s86, 0
	s_cselect_b64 vcc, -1, 0
	s_or_b32 s30, s86, s19
	s_ashr_i32 s31, s30, 31
	v_readlane_b32 s8, v253, 41
	s_lshl_b64 s[30:31], s[30:31], 12
	v_readlane_b32 s10, v253, 43
	v_add_u32_e32 v0, s87, v54
	v_readlane_b32 s11, v253, 44
	s_add_u32 s28, s10, s30
	v_cmp_lt_i32_e64 s[88:89], s15, v0
	s_addc_u32 s40, s11, s31
	s_lshl_b32 s91, s85, 6
	s_lshl_b32 s41, s85, 8
	v_cndmask_b32_e64 v2, v176, v177, s[88:89]
	v_readlane_b32 s9, v253, 42
	s_add_u32 s88, s28, s41
	v_sub_u32_e32 v2, v2, v0
	s_addc_u32 s89, s40, 0
	v_readlane_b32 s8, v253, 45
	v_cndmask_b32_e32 v0, v2, v0, vcc
	s_mulk_i32 s90, 0x4100
	v_readlane_b32 s9, v253, 46
	s_add_u32 s28, s8, s30
	v_add_u32_e32 v2, s90, v0
	s_addc_u32 s31, s9, s31
	s_add_u32 s30, s28, s41
	v_ashrrev_i32_e32 v3, 31, v2
	v_readlane_b32 s40, v251, 23
	v_lshlrev_b64 v[2:3], 8, v[2:3]
	v_readlane_b32 s41, v251, 24
	s_addc_u32 s31, s31, 0
	v_lshl_add_u64 v[4:5], s[36:37], 0, v[2:3]
	s_lshl_b32 s28, s86, 7
	v_lshl_add_u64 v[2:3], s[40:41], 0, v[2:3]
	v_lshl_add_u64 v[4:5], v[4:5], 0, s[28:29]
	v_lshl_add_u64 v[2:3], v[2:3], 0, s[28:29]
	s_lshl_b32 s28, s86, 17
	v_readlane_b32 s40, v251, 27
	s_add_u32 s40, s40, s28
	v_readlane_b32 s28, v251, 28
	v_mov_b32_e32 v41, v1
	s_addc_u32 s41, s28, 0
	v_or_b32_e32 v0, s91, v37
	v_lshl_add_u64 v[30:31], v[4:5], 0, v[40:41]
	v_lshl_add_u64 v[46:47], v[2:3], 0, v[40:41]
	v_lshl_add_u64 v[18:19], s[40:41], 0, v[40:41]
	v_lshlrev_b32_e32 v41, 6, v0
	s_mov_b64 s[40:41], 0x40000
	v_or_b32_e32 v0, v41, v71
	v_lshl_add_u64 v[20:21], v[18:19], 0, s[40:41]
	v_lshlrev_b32_e32 v0, 1, v0
	v_lshl_add_u64 v[48:49], v[18:19], 0, v[0:1]
	v_lshl_add_u64 v[50:51], v[20:21], 0, v[0:1]
	v_or_b32_e32 v0, v41, v77
	v_lshlrev_b32_e32 v0, 1, v0
	v_lshl_add_u64 v[26:27], v[18:19], 0, v[0:1]
	v_lshl_add_u64 v[28:29], v[20:21], 0, v[0:1]
	v_readfirstlane_b32 s40, v35
	s_lshr_b32 s40, s40, 6
	s_and_b32 s41, s40, 1
	s_lshr_b32 s40, s40, 1
	s_lshl_b32 s12, s41, 6
	s_mov_b32 s13, 0
	v_lshl_add_u64 v[30:31], v[30:31], 0, s[12:13]
	v_lshl_add_u64 v[46:47], v[46:47], 0, s[12:13]
	s_cmp_lt_u32 s40, 2
	s_cselect_b64 s[98:99], -1, 0
	s_and_b32 s12, s40, 1
	s_lshl_b32 s12, s12, 6
	v_cndmask_b32_e64 v26, v26, v48, s[98:99]
	v_cndmask_b32_e64 v27, v27, v49, s[98:99]
	v_cndmask_b32_e64 v28, v28, v50, s[98:99]
	v_cndmask_b32_e64 v29, v29, v51, s[98:99]
	v_lshl_add_u64 v[26:27], v[26:27], 0, s[12:13]
	v_lshl_add_u64 v[28:29], v[28:29], 0, s[12:13]
	global_load_dwordx4 v[2:5], v[30:31], off
	global_load_dwordx4 v[6:9], v[46:47], off
	global_load_dwordx4 v[10:13], v[26:27], off
	global_load_dwordx4 v[14:17], v[28:29], off
	global_load_dword v244, v208, s[88:89]
	global_load_dword v245, v208, s[30:31]
	global_load_dword v246, v209, s[88:89]
	global_load_dword v247, v209, s[30:31]
	v_readlane_b32 s8, v254, 61
	v_readlane_b32 s9, v254, 62
	v_readlane_b32 s10, v253, 47
	v_readlane_b32 s11, v253, 48
	v_and_b32_e32 v18, 63, v35
	v_lshlrev_b32_e32 v18, 4, v18
	s_lshl_b32 s12, s40, 12
	s_lshl_b32 s28, s41, 11
	s_add_i32 s28, s28, s12
	v_add_u32_e32 v19, s28, v18
	s_lshl_b32 s28, s41, 13
	s_lshl_b32 s13, s40, 11
	s_add_i32 s28, s28, s13
	s_addk_i32 s28, 0x4000
	v_add_u32_e32 v20, s28, v18
	s_waitcnt vmcnt(4)
	ds_write_b128 v19, v[2:5]
	ds_write_b128 v19, v[6:9] offset:1024
	ds_write_b128 v20, v[10:13]
	ds_write_b128 v20, v[14:17] offset:1024
	s_waitcnt lgkmcnt(0)
	s_barrier
	v_add_u32_e32 v19, s12, v18
	s_lshl_b32 s28, s41, 13
	s_addk_i32 s28, 0x4000
	v_add_u32_e32 v20, s28, v18
	ds_read_b128 v[2:5], v19
	ds_read_b128 v[6:9], v19 offset:1024
	ds_read_b128 v[212:215], v20
	ds_read_b128 v[216:219], v20 offset:1024
	ds_read_b128 v[10:13], v19 offset:2048
	ds_read_b128 v[14:17], v19 offset:3072
	ds_read_b128 v[220:223], v20 offset:2048
	ds_read_b128 v[224:227], v20 offset:3072
	ds_read_b128 v[228:231], v20 offset:4096
	ds_read_b128 v[232:235], v20 offset:5120
	ds_read_b128 v[236:239], v20 offset:6144
	ds_read_b128 v[240:243], v20 offset:7168
	s_waitcnt lgkmcnt(8)
	v_mfma_f32_16x16x32_bf16 v[22:25], v[2:5], v[212:215], 0
	v_mfma_f32_16x16x32_bf16 v[26:29], v[6:9], v[216:219], 0
	s_waitcnt lgkmcnt(4)
	v_mfma_f32_16x16x32_bf16 v[22:25], v[10:13], v[220:223], v[22:25]
	v_mfma_f32_16x16x32_bf16 v[26:29], v[14:17], v[224:227], v[26:29]
	s_waitcnt lgkmcnt(2)
	v_mfma_f32_16x16x32_bf16 v[18:21], v[2:5], v[228:231], 0
	v_mfma_f32_16x16x32_bf16 v[46:49], v[6:9], v[232:235], 0
	s_waitcnt lgkmcnt(0)
	v_mfma_f32_16x16x32_bf16 v[18:21], v[10:13], v[236:239], v[18:21]
	v_mfma_f32_16x16x32_bf16 v[46:49], v[14:17], v[240:243], v[46:49]
	s_waitcnt vmcnt(0)
; __device__ __forceinline__ float sigm(float x) { return __builtin_amdgcn_rcpf(1.f + __expf(-x)); }
; __device__ __forceinline__ void ph_r7_ca(const P& p, int j, int win, char* smem) {
;     ...
;         const int ch = 16 * tj + l15; const float w0v = w0[ch], a0v = a0[ch];
; #pragma unroll
;         for (int jj = 0; jj < 4; jj++) { const int tau = 16 * ti + 4 * q4 + jj; LW[tau * 64 + ch] = -0.6065306597126334f * sigm(w0v + aw[jj]); AT[tau * 64 + ch] = sigm(a0v + aa[jj]); }
;       }
;     }
;     __syncthreads();
;     if (tid < 64) { float acc = 0.f;
; #pragma unroll 8
;       for (int t = 0; t < 64; t++) { acc += LW[t * 64 + tid]; LW[t * 64 + tid] = acc; } }
;     __syncthreads();
;     {
;       const int tau = tid >> 3, sc = tid & 7, col = h * 64 + sc * 8; const int row = rowmap(d, b, 64 * c + tau);
;       const bfr* rp = RK + (size_t)row * 4096 + col; uint4 pr = *(const uint4*)rp, pk = *(const uint4*)(rp + 1024);
	s_nop 3
	v_add_f32_e32 v22, v22, v244
	v_add_f32_e32 v23, v23, v244
	v_add_f32_e32 v24, v24, v244
	v_add_f32_e32 v25, v25, v244
	v_mul_f32_e32 v22, 0xbfb8aa3b, v22
	v_mul_f32_e32 v23, 0xbfb8aa3b, v23
	v_mul_f32_e32 v24, 0xbfb8aa3b, v24
	v_mul_f32_e32 v25, 0xbfb8aa3b, v25
	v_exp_f32_e32 v22, v22
	v_exp_f32_e32 v23, v23
	v_exp_f32_e32 v24, v24
	v_exp_f32_e32 v25, v25
	v_add_f32_e32 v22, 1.0, v22
	v_add_f32_e32 v23, 1.0, v23
	v_add_f32_e32 v24, 1.0, v24
	v_add_f32_e32 v25, 1.0, v25
	v_rcp_f32_e32 v22, v22
	v_rcp_f32_e32 v23, v23
	v_rcp_f32_e32 v24, v24
	v_rcp_f32_e32 v25, v25
	v_mul_f32_e32 v22, 0xbf1b4598, v22
	v_mul_f32_e32 v23, 0xbf1b4598, v23
	v_mul_f32_e32 v24, 0xbf1b4598, v24
	v_mul_f32_e32 v25, 0xbf1b4598, v25
	v_add_f32_e32 v26, v26, v245
	v_add_f32_e32 v27, v27, v245
	v_add_f32_e32 v28, v28, v245
	v_add_f32_e32 v29, v29, v245
	v_mul_f32_e32 v26, 0xbfb8aa3b, v26
	v_mul_f32_e32 v27, 0xbfb8aa3b, v27
	v_mul_f32_e32 v28, 0xbfb8aa3b, v28
	v_mul_f32_e32 v29, 0xbfb8aa3b, v29
	v_exp_f32_e32 v26, v26
	v_exp_f32_e32 v27, v27
	v_exp_f32_e32 v28, v28
	v_exp_f32_e32 v29, v29
	v_add_f32_e32 v26, 1.0, v26
	v_add_f32_e32 v27, 1.0, v27
	v_add_f32_e32 v28, 1.0, v28
	v_add_f32_e32 v29, 1.0, v29
	v_rcp_f32_e32 v26, v26
	v_rcp_f32_e32 v27, v27
	v_rcp_f32_e32 v28, v28
	v_rcp_f32_e32 v29, v29
	ds_write_b32 v73, v26
	ds_write2st64_b32 v72, v22, v23 offset0:252 offset1:253
	ds_write_b32 v74, v27
	ds_write_b32 v72, v24 offset:65024
	ds_write_b32 v75, v28
	ds_write_b32 v72, v25 offset:65280
	ds_write_b32 v76, v29
	v_add_f32_e32 v18, v18, v246
	v_add_f32_e32 v19, v19, v246
	v_add_f32_e32 v20, v20, v246
	v_add_f32_e32 v21, v21, v246
	v_mul_f32_e32 v18, 0xbfb8aa3b, v18
	v_mul_f32_e32 v19, 0xbfb8aa3b, v19
	v_mul_f32_e32 v20, 0xbfb8aa3b, v20
	v_mul_f32_e32 v21, 0xbfb8aa3b, v21
	v_exp_f32_e32 v18, v18
	v_exp_f32_e32 v19, v19
	v_exp_f32_e32 v20, v20
	v_exp_f32_e32 v21, v21
	v_add_f32_e32 v18, 1.0, v18
	v_add_f32_e32 v19, 1.0, v19
	v_add_f32_e32 v20, 1.0, v20
	v_add_f32_e32 v21, 1.0, v21
	v_rcp_f32_e32 v18, v18
	v_rcp_f32_e32 v19, v19
	v_rcp_f32_e32 v20, v20
	v_rcp_f32_e32 v21, v21
	v_mul_f32_e32 v18, 0xbf1b4598, v18
	v_mul_f32_e32 v19, 0xbf1b4598, v19
	v_mul_f32_e32 v20, 0xbf1b4598, v20
	v_mul_f32_e32 v21, 0xbf1b4598, v21
	v_add_f32_e32 v46, v46, v247
	v_add_f32_e32 v47, v47, v247
	v_add_f32_e32 v48, v48, v247
	v_add_f32_e32 v49, v49, v247
	v_mul_f32_e32 v46, 0xbfb8aa3b, v46
	v_mul_f32_e32 v47, 0xbfb8aa3b, v47
	v_mul_f32_e32 v48, 0xbfb8aa3b, v48
	v_mul_f32_e32 v49, 0xbfb8aa3b, v49
	v_exp_f32_e32 v46, v46
	v_exp_f32_e32 v47, v47
	v_exp_f32_e32 v48, v48
	v_exp_f32_e32 v49, v49
	v_add_f32_e32 v46, 1.0, v46
	v_add_f32_e32 v47, 1.0, v47
	v_add_f32_e32 v48, 1.0, v48
	v_add_f32_e32 v49, 1.0, v49
	v_rcp_f32_e32 v46, v46
	v_rcp_f32_e32 v47, v47
	v_rcp_f32_e32 v48, v48
	v_rcp_f32_e32 v49, v49
	ds_write_b32 v79, v46
	ds_write2st64_b32 v78, v18, v19 offset0:252 offset1:253
	ds_write_b32 v80, v47
	ds_write_b32 v78, v20 offset:65024
	ds_write_b32 v81, v48
	ds_write_b32 v78, v21 offset:65280
	ds_write_b32 v82, v49
	s_waitcnt lgkmcnt(0)
	s_barrier
	v_add_u32_e32 v0, s87, v52
	v_cmp_lt_i32_e64 s[88:89], s15, v0
	v_or_b32_e32 v12, s91, v56
	s_nop 0
	v_cndmask_b32_e64 v2, v176, v177, s[88:89]
	v_sub_u32_e32 v2, v2, v0
	v_cndmask_b32_e32 v0, v2, v0, vcc
	v_add_u32_e32 v6, s90, v0
	v_ashrrev_i32_e32 v7, 31, v6
	v_lshlrev_b64 v[2:3], 13, v[6:7]
	v_lshl_add_u64 v[2:3], s[38:39], 0, v[2:3]
	v_lshlrev_b32_e32 v0, 1, v12
	v_lshl_add_u64 v[8:9], v[2:3], 0, v[0:1]
	v_lshlrev_b32_e32 v0, 2, v12
	global_load_dwordx4 v[2:5], v[8:9], off
	global_load_dwordx4 v[8:11], v[8:9], off offset:2048
	global_load_dwordx4 v[244:247], v0, s[92:93] offset:16
	global_load_dwordx4 v[14:17], v0, s[92:93]
	s_and_saveexec_b64 s[30:31], s[8:9]
	s_cbranch_execz .LBB0_190
; __device__ __forceinline__ void ph_r7_ca(const P& p, int j, int win, char* smem) {
;     ...
;     if (tid < 64) { float acc = 0.f;
; #pragma unroll 8
;       for (int t = 0; t < 64; t++) { acc += LW[t * 64 + tid]; LW[t * 64 + tid] = acc; } }
	v_add_u32_e32 v26, 0xfc00, v55
	v_mov_b32_e32 v27, 0
	ds_read2st64_b32 v[212:213], v26 offset0:0 offset1:1
	ds_read2st64_b32 v[214:215], v26 offset0:2 offset1:3
	ds_read2st64_b32 v[216:217], v26 offset0:4 offset1:5
	ds_read2st64_b32 v[218:219], v26 offset0:6 offset1:7
	ds_read2st64_b32 v[220:221], v26 offset0:8 offset1:9
	ds_read2st64_b32 v[222:223], v26 offset0:10 offset1:11
	ds_read2st64_b32 v[224:225], v26 offset0:12 offset1:13
	ds_read2st64_b32 v[226:227], v26 offset0:14 offset1:15
	ds_read2st64_b32 v[228:229], v26 offset0:16 offset1:17
	ds_read2st64_b32 v[230:231], v26 offset0:18 offset1:19
	ds_read2st64_b32 v[232:233], v26 offset0:20 offset1:21
	ds_read2st64_b32 v[234:235], v26 offset0:22 offset1:23
	ds_read2st64_b32 v[236:237], v26 offset0:24 offset1:25
	ds_read2st64_b32 v[238:239], v26 offset0:26 offset1:27
	ds_read2st64_b32 v[240:241], v26 offset0:28 offset1:29
	ds_read2st64_b32 v[242:243], v26 offset0:30 offset1:31
	s_waitcnt lgkmcnt(8)
	v_add_f32_e32 v212, v27, v212
	v_add_f32_e32 v213, v212, v213
	v_add_f32_e32 v214, v213, v214
	v_add_f32_e32 v215, v214, v215
	v_add_f32_e32 v216, v215, v216
	v_add_f32_e32 v217, v216, v217
	v_add_f32_e32 v218, v217, v218
	v_add_f32_e32 v219, v218, v219
	v_add_f32_e32 v220, v219, v220
	v_add_f32_e32 v221, v220, v221
	v_add_f32_e32 v222, v221, v222
	v_add_f32_e32 v223, v222, v223
	v_add_f32_e32 v224, v223, v224
	v_add_f32_e32 v225, v224, v225
	v_add_f32_e32 v226, v225, v226
	v_add_f32_e32 v227, v226, v227
	v_mov_b32_e32 v27, v227
	ds_write2st64_b32 v26, v212, v213 offset0:0 offset1:1
	ds_write2st64_b32 v26, v214, v215 offset0:2 offset1:3
	ds_write2st64_b32 v26, v216, v217 offset0:4 offset1:5
	ds_write2st64_b32 v26, v218, v219 offset0:6 offset1:7
	ds_write2st64_b32 v26, v220, v221 offset0:8 offset1:9
	ds_write2st64_b32 v26, v222, v223 offset0:10 offset1:11
	ds_write2st64_b32 v26, v224, v225 offset0:12 offset1:13
	ds_write2st64_b32 v26, v226, v227 offset0:14 offset1:15
	s_waitcnt lgkmcnt(8)
	ds_read2st64_b32 v[212:213], v26 offset0:32 offset1:33
	ds_read2st64_b32 v[214:215], v26 offset0:34 offset1:35
	ds_read2st64_b32 v[216:217], v26 offset0:36 offset1:37
	ds_read2st64_b32 v[218:219], v26 offset0:38 offset1:39
	ds_read2st64_b32 v[220:221], v26 offset0:40 offset1:41
	ds_read2st64_b32 v[222:223], v26 offset0:42 offset1:43
	ds_read2st64_b32 v[224:225], v26 offset0:44 offset1:45
	ds_read2st64_b32 v[226:227], v26 offset0:46 offset1:47
	v_add_f32_e32 v228, v27, v228
	v_add_f32_e32 v229, v228, v229
	v_add_f32_e32 v230, v229, v230
	v_add_f32_e32 v231, v230, v231
	v_add_f32_e32 v232, v231, v232
	v_add_f32_e32 v233, v232, v233
	v_add_f32_e32 v234, v233, v234
	v_add_f32_e32 v235, v234, v235
	v_add_f32_e32 v236, v235, v236
	v_add_f32_e32 v237, v236, v237
	v_add_f32_e32 v238, v237, v238
	v_add_f32_e32 v239, v238, v239
	v_add_f32_e32 v240, v239, v240
	v_add_f32_e32 v241, v240, v241
	v_add_f32_e32 v242, v241, v242
	v_add_f32_e32 v243, v242, v243
	v_mov_b32_e32 v27, v243
	ds_write2st64_b32 v26, v228, v229 offset0:16 offset1:17
	ds_write2st64_b32 v26, v230, v231 offset0:18 offset1:19
	ds_write2st64_b32 v26, v232, v233 offset0:20 offset1:21
	ds_write2st64_b32 v26, v234, v235 offset0:22 offset1:23
	ds_write2st64_b32 v26, v236, v237 offset0:24 offset1:25
	ds_write2st64_b32 v26, v238, v239 offset0:26 offset1:27
	ds_write2st64_b32 v26, v240, v241 offset0:28 offset1:29
	ds_write2st64_b32 v26, v242, v243 offset0:30 offset1:31
	s_waitcnt lgkmcnt(8)
	ds_read2st64_b32 v[228:229], v26 offset0:48 offset1:49
	ds_read2st64_b32 v[230:231], v26 offset0:50 offset1:51
	ds_read2st64_b32 v[232:233], v26 offset0:52 offset1:53
	ds_read2st64_b32 v[234:235], v26 offset0:54 offset1:55
	ds_read2st64_b32 v[236:237], v26 offset0:56 offset1:57
	ds_read2st64_b32 v[238:239], v26 offset0:58 offset1:59
	ds_read2st64_b32 v[240:241], v26 offset0:60 offset1:61
	ds_read2st64_b32 v[242:243], v26 offset0:62 offset1:63
	v_add_f32_e32 v212, v27, v212
	v_add_f32_e32 v213, v212, v213
	v_add_f32_e32 v214, v213, v214
	v_add_f32_e32 v215, v214, v215
	v_add_f32_e32 v216, v215, v216
	v_add_f32_e32 v217, v216, v217
	v_add_f32_e32 v218, v217, v218
	v_add_f32_e32 v219, v218, v219
	v_add_f32_e32 v220, v219, v220
	v_add_f32_e32 v221, v220, v221
	v_add_f32_e32 v222, v221, v222
	v_add_f32_e32 v223, v222, v223
	v_add_f32_e32 v224, v223, v224
	v_add_f32_e32 v225, v224, v225
	v_add_f32_e32 v226, v225, v226
	v_add_f32_e32 v227, v226, v227
	v_mov_b32_e32 v27, v227
	ds_write2st64_b32 v26, v212, v213 offset0:32 offset1:33
	ds_write2st64_b32 v26, v214, v215 offset0:34 offset1:35
	ds_write2st64_b32 v26, v216, v217 offset0:36 offset1:37
	ds_write2st64_b32 v26, v218, v219 offset0:38 offset1:39
	ds_write2st64_b32 v26, v220, v221 offset0:40 offset1:41
	ds_write2st64_b32 v26, v222, v223 offset0:42 offset1:43
	ds_write2st64_b32 v26, v224, v225 offset0:44 offset1:45
	ds_write2st64_b32 v26, v226, v227 offset0:46 offset1:47
	s_waitcnt lgkmcnt(8)
	v_add_f32_e32 v228, v27, v228
	v_add_f32_e32 v229, v228, v229
	v_add_f32_e32 v230, v229, v230
	v_add_f32_e32 v231, v230, v231
	v_add_f32_e32 v232, v231, v232
	v_add_f32_e32 v233, v232, v233
	v_add_f32_e32 v234, v233, v234
	v_add_f32_e32 v235, v234, v235
	v_add_f32_e32 v236, v235, v236
	v_add_f32_e32 v237, v236, v237
	v_add_f32_e32 v238, v237, v238
	v_add_f32_e32 v239, v238, v239
	v_add_f32_e32 v240, v239, v240
	v_add_f32_e32 v241, v240, v241
	v_add_f32_e32 v242, v241, v242
	v_add_f32_e32 v243, v242, v243
	v_mov_b32_e32 v27, v243
	ds_write2st64_b32 v26, v228, v229 offset0:48 offset1:49
	ds_write2st64_b32 v26, v230, v231 offset0:50 offset1:51
	ds_write2st64_b32 v26, v232, v233 offset0:52 offset1:53
	ds_write2st64_b32 v26, v234, v235 offset0:54 offset1:55
	ds_write2st64_b32 v26, v236, v237 offset0:56 offset1:57
	ds_write2st64_b32 v26, v238, v239 offset0:58 offset1:59
	ds_write2st64_b32 v26, v240, v241 offset0:60 offset1:61
	ds_write2st64_b32 v26, v242, v243 offset0:62 offset1:63

; #define PG8_STAGE(bufoff, gbase, voff) do { _Pragma("unroll") for (int _i = 0; _i < 2; ++_i) \
;     __builtin_amdgcn_global_load_lds((const unsigned*)((const char*)(gbase) + (voff)[_i]), (PG8_LAS unsigned*)(lds + (bufoff) + ldsw + _i * 8192), 16, 0, 0); } while (0)
; #define PG8_LDA(dst, b, h) do { _Pragma("unroll") for (int m = 0; m < 4; ++m) _Pragma("unroll") for (int k = 0; k < 2; ++k) dst[m][k] = *(const PG8_LAS bf16x8*)(lds + PG8_SA(b, h) + aoff + m * 2048 + k * 1024); } while (0)
; #define PG8_LDB(dst, b, h) do { _Pragma("unroll") for (int n = 0; n < 2; ++n) _Pragma("unroll") for (int k = 0; k < 2; ++k) dst[n][k] = *(const PG8_LAS bf16x8*)(lds + PG8_SB(b, h) + boff + n * 2048 + k * 1024); } while (0)
; #define PG8_MMA(ai, bj, At, Bt) do { __builtin_amdgcn_s_setprio(1); _Pragma("unroll") for (int m = 0; m < 4; ++m) _Pragma("unroll") for (int n = 0; n < 2; ++n) _Pragma("unroll") for (int k = 0; k < 2; ++k) \
;     acc[ai][bj][m][n] = __builtin_amdgcn_mfma_f32_16x16x32_bf16(Bt[n][k], At[m][k], acc[ai][bj][m][n], 0, 0, 0); __builtin_amdgcn_s_setprio(0); } while (0)
; #define PG8_WAIT_V(n) asm volatile("s_waitcnt vmcnt(" #n ")" ::: "memory")
; #define PG8_WAIT_L(n) asm volatile("s_waitcnt lgkmcnt(" #n ")" ::: "memory")
; #define PG8_BAR __builtin_amdgcn_s_barrier()
; #define PG8_SCHED __builtin_amdgcn_sched_barrier(0)
; template <class Epi>
; __device__ __forceinline__ void gemm_phase(PG8_LAS unsigned char* lds, const Gemm g, const StaticOrder& S, const Epi& E) {
;     ...
;       PG8_LDB(B0, 0, 0); PG8_SCHED; PG8_LDA(At, 0, 0); PG8_STAGE(PG8_SA(1, 1), a1 + hstep, voffA);
;       PG8_WAIT_L(8); PG8_BAR; PG8_WAIT_L(0); PG8_MMA(0, 0, At, B0); PG8_BAR; PG8_SCHED;
;       PG8_LDB(B1, 0, 1); PG8_STAGE(PG8_SB(0, 0), b2, voffB);
;       PG8_BAR; PG8_WAIT_L(0); PG8_MMA(0, 1, At, B1); PG8_BAR;
;       PG8_LDA(At, 0, 1); PG8_STAGE(PG8_SA(0, 0), a2, voffA);
;       PG8_BAR; PG8_WAIT_L(0); PG8_MMA(1, 0, At, B0); PG8_BAR; PG8_SCHED;
;       PG8_STAGE(PG8_SB(0, 1), b2 + hstep, voffB);
;       PG8_WAIT_V(6); PG8_BAR; PG8_MMA(1, 1, At, B1); PG8_BAR;
.LBB0_1046:
	s_add_u32 s50, s48, 0x100
	s_addc_u32 s51, s49, 0
	s_add_i32 s66, 0, 0x10000
	v_add_u32_e32 v158, s66, v160
	ds_read_b128 v[154:157], v158
	ds_read_b128 v[164:167], v158 offset:1024
	ds_read_b128 v[188:191], v158 offset:2048
	ds_read_b128 v[192:195], v158 offset:3072
	s_cmp_eq_u32 s65, 28
	s_cselect_b32 s55, s11, s51
	s_cselect_b32 s54, s43, s50
	s_cselect_b32 s53, s9, s64
	s_cselect_b32 s52, s47, s63
	v_lshl_add_u64 v[158:159], s[48:49], 0, v[150:151]
	s_add_i32 m0, s56, 0xc000
	ds_read_b128 v[196:199], v162
	ds_read_b128 v[200:203], v162 offset:1024
	ds_read_b128 v[204:207], v162 offset:2048
	ds_read_b128 v[208:211], v162 offset:3072
	ds_read_b128 v[212:215], v162 offset:4096
	ds_read_b128 v[216:219], v162 offset:5120
	ds_read_b128 v[220:223], v162 offset:6144
	ds_read_b128 v[224:227], v162 offset:7168
	global_load_lds_dwordx4 v[158:159], off
	v_lshl_add_u64 v[158:159], s[48:49], 0, v[152:153]
	s_add_i32 m0, s56, 0xe000
	s_nop 0
	global_load_lds_dwordx4 v[158:159], off
	s_waitcnt lgkmcnt(8)
	s_barrier
	s_waitcnt lgkmcnt(0)
	s_setprio 1
	s_waitcnt lgkmcnt(0)
	v_mfma_f32_16x16x32_bf16 v[126:129], v[154:157], v[196:199], v[126:129]
	v_mfma_f32_16x16x32_bf16 v[122:125], v[188:191], v[196:199], v[122:125]
	v_mfma_f32_16x16x32_bf16 v[110:113], v[154:157], v[204:207], v[110:113]
	v_mfma_f32_16x16x32_bf16 v[106:109], v[188:191], v[204:207], v[106:109]
	v_mfma_f32_16x16x32_bf16 v[94:97], v[154:157], v[212:215], v[94:97]
	v_mfma_f32_16x16x32_bf16 v[90:93], v[188:191], v[212:215], v[90:93]
	v_mfma_f32_16x16x32_bf16 v[78:81], v[154:157], v[220:223], v[78:81]
	v_mfma_f32_16x16x32_bf16 v[74:77], v[188:191], v[220:223], v[74:77]
	v_mfma_f32_16x16x32_bf16 v[126:129], v[164:167], v[200:203], v[126:129]
	v_mfma_f32_16x16x32_bf16 v[122:125], v[192:195], v[200:203], v[122:125]
	v_mfma_f32_16x16x32_bf16 v[110:113], v[164:167], v[208:211], v[110:113]
	v_mfma_f32_16x16x32_bf16 v[106:109], v[192:195], v[208:211], v[106:109]
	v_mfma_f32_16x16x32_bf16 v[94:97], v[164:167], v[216:219], v[94:97]
	v_mfma_f32_16x16x32_bf16 v[90:93], v[192:195], v[216:219], v[90:93]
	v_mfma_f32_16x16x32_bf16 v[78:81], v[164:167], v[224:227], v[78:81]
	v_mfma_f32_16x16x32_bf16 v[74:77], v[192:195], v[224:227], v[74:77]
	s_setprio 0
	s_barrier
	s_add_i32 s67, 0, 0x14000
	v_add_u32_e32 v158, s67, v160
	s_add_i32 s48, s66, s28
	ds_read_b128 v[228:231], v158
	ds_read_b128 v[232:235], v158 offset:1024
	ds_read_b128 v[236:239], v158 offset:2048
	ds_read_b128 v[240:243], v158 offset:3072
	v_lshl_add_u64 v[158:159], s[52:53], 0, v[0:1]
	s_mov_b32 m0, s48
	v_lshl_add_u64 v[178:179], s[52:53], 0, v[148:149]
	global_load_lds_dwordx4 v[158:159], off
	s_add_i32 m0, s48, 0x2000
	s_nop 0
	global_load_lds_dwordx4 v[178:179], off
	s_barrier
	s_waitcnt lgkmcnt(0)
	s_setprio 1
	s_waitcnt lgkmcnt(0)
	v_mfma_f32_16x16x32_bf16 v[118:121], v[228:231], v[196:199], v[118:121]
	v_mfma_f32_16x16x32_bf16 v[114:117], v[236:239], v[196:199], v[114:117]
	v_mfma_f32_16x16x32_bf16 v[102:105], v[228:231], v[204:207], v[102:105]
	v_mfma_f32_16x16x32_bf16 v[98:101], v[236:239], v[204:207], v[98:101]
	v_mfma_f32_16x16x32_bf16 v[86:89], v[228:231], v[212:215], v[86:89]
	v_mfma_f32_16x16x32_bf16 v[82:85], v[236:239], v[212:215], v[82:85]
	v_mfma_f32_16x16x32_bf16 v[70:73], v[228:231], v[220:223], v[70:73]
	v_mfma_f32_16x16x32_bf16 v[66:69], v[236:239], v[220:223], v[66:69]
	v_mfma_f32_16x16x32_bf16 v[118:121], v[232:235], v[200:203], v[118:121]
	v_mfma_f32_16x16x32_bf16 v[114:117], v[240:243], v[200:203], v[114:117]
	v_mfma_f32_16x16x32_bf16 v[102:105], v[232:235], v[208:211], v[102:105]
	v_mfma_f32_16x16x32_bf16 v[98:101], v[240:243], v[208:211], v[98:101]
	v_mfma_f32_16x16x32_bf16 v[86:89], v[232:235], v[216:219], v[86:89]
	v_mfma_f32_16x16x32_bf16 v[82:85], v[240:243], v[216:219], v[82:85]
	v_mfma_f32_16x16x32_bf16 v[70:73], v[232:235], v[224:227], v[70:73]
	v_mfma_f32_16x16x32_bf16 v[66:69], v[240:243], v[224:227], v[66:69]
	s_setprio 0
	s_mov_b32 m0, s56
	v_lshl_add_u64 v[244:245], s[54:55], 0, v[0:1]
	s_barrier
	ds_read_b128 v[196:199], v162 offset:16384
	ds_read_b128 v[200:203], v162 offset:17408
	ds_read_b128 v[204:207], v162 offset:18432
	ds_read_b128 v[208:211], v162 offset:19456
	ds_read_b128 v[212:215], v162 offset:20480
	ds_read_b128 v[216:219], v162 offset:21504
	ds_read_b128 v[220:223], v162 offset:22528
	ds_read_b128 v[224:227], v162 offset:23552
	global_load_lds_dwordx4 v[244:245], off
	v_lshl_add_u64 v[246:247], s[54:55], 0, v[148:149]
	s_mov_b32 m0, s57
	s_nop 0
	global_load_lds_dwordx4 v[246:247], off
	s_barrier
	s_waitcnt lgkmcnt(0)
	s_setprio 1
	s_waitcnt lgkmcnt(0)
	v_mfma_f32_16x16x32_bf16 v[62:65], v[154:157], v[196:199], v[62:65]
	v_mfma_f32_16x16x32_bf16 v[58:61], v[188:191], v[196:199], v[58:61]
	v_mfma_f32_16x16x32_bf16 v[46:49], v[154:157], v[204:207], v[46:49]
	v_mfma_f32_16x16x32_bf16 v[42:45], v[188:191], v[204:207], v[42:45]
	v_mfma_f32_16x16x32_bf16 v[30:33], v[154:157], v[212:215], v[30:33]
	v_mfma_f32_16x16x32_bf16 v[26:29], v[188:191], v[212:215], v[26:29]
	v_mfma_f32_16x16x32_bf16 v[14:17], v[154:157], v[220:223], v[14:17]
	v_mfma_f32_16x16x32_bf16 v[10:13], v[188:191], v[220:223], v[10:13]
	v_mfma_f32_16x16x32_bf16 v[62:65], v[164:167], v[200:203], v[62:65]
	v_mfma_f32_16x16x32_bf16 v[58:61], v[192:195], v[200:203], v[58:61]
	v_mfma_f32_16x16x32_bf16 v[46:49], v[164:167], v[208:211], v[46:49]
	v_mfma_f32_16x16x32_bf16 v[42:45], v[192:195], v[208:211], v[42:45]
	v_mfma_f32_16x16x32_bf16 v[30:33], v[164:167], v[216:219], v[30:33]
	v_mfma_f32_16x16x32_bf16 v[26:29], v[192:195], v[216:219], v[26:29]
	v_mfma_f32_16x16x32_bf16 v[14:17], v[164:167], v[224:227], v[14:17]
	v_mfma_f32_16x16x32_bf16 v[10:13], v[192:195], v[224:227], v[10:13]
	s_setprio 0
	s_barrier
; #define PG8_STAGE(bufoff, gbase, voff) do { _Pragma("unroll") for (int _i = 0; _i < 2; ++_i) \
;     __builtin_amdgcn_global_load_lds((const unsigned*)((const char*)(gbase) + (voff)[_i]), (PG8_LAS unsigned*)(lds + (bufoff) + ldsw + _i * 8192), 16, 0, 0); } while (0)
; #define PG8_LDA(dst, b, h) do { _Pragma("unroll") for (int m = 0; m < 4; ++m) _Pragma("unroll") for (int k = 0; k < 2; ++k) dst[m][k] = *(const PG8_LAS bf16x8*)(lds + PG8_SA(b, h) + aoff + m * 2048 + k * 1024); } while (0)
; #define PG8_LDB(dst, b, h) do { _Pragma("unroll") for (int n = 0; n < 2; ++n) _Pragma("unroll") for (int k = 0; k < 2; ++k) dst[n][k] = *(const PG8_LAS bf16x8*)(lds + PG8_SB(b, h) + boff + n * 2048 + k * 1024); } while (0)
; #define PG8_MMA(ai, bj, At, Bt) do { __builtin_amdgcn_s_setprio(1); _Pragma("unroll") for (int m = 0; m < 4; ++m) _Pragma("unroll") for (int n = 0; n < 2; ++n) _Pragma("unroll") for (int k = 0; k < 2; ++k) \
;     acc[ai][bj][m][n] = __builtin_amdgcn_mfma_f32_16x16x32_bf16(Bt[n][k], At[m][k], acc[ai][bj][m][n], 0, 0, 0); __builtin_amdgcn_s_setprio(0); } while (0)
; #define PG8_WAIT_V(n) asm volatile("s_waitcnt vmcnt(" #n ")" ::: "memory")
; #define PG8_WAIT_L(n) asm volatile("s_waitcnt lgkmcnt(" #n ")" ::: "memory")
; #define PG8_BAR __builtin_amdgcn_s_barrier()
; #define PG8_SCHED __builtin_amdgcn_sched_barrier(0)
; template <class Epi>
; __device__ __forceinline__ void gemm_phase(PG8_LAS unsigned char* lds, const Gemm g, const StaticOrder& S, const Epi& E) {
;     ...
;       PG8_WAIT_V(6); PG8_BAR; PG8_MMA(1, 1, At, B1); PG8_BAR;
;       PG8_LDB(B0, 1, 0); PG8_SCHED; PG8_LDA(At, 1, 0); PG8_STAGE(PG8_SA(0, 1), a2 + hstep, voffA);
;       PG8_WAIT_L(8); PG8_BAR; PG8_WAIT_L(0); PG8_MMA(0, 0, At, B0); PG8_BAR; PG8_SCHED;
;       PG8_LDB(B1, 1, 1); PG8_STAGE(PG8_SB(1, 0), b3, voffB);
;       PG8_BAR; PG8_WAIT_L(0); PG8_MMA(0, 1, At, B1); PG8_BAR;
;       PG8_LDA(At, 1, 1); PG8_STAGE(PG8_SA(1, 0), a3, voffA);
;       PG8_BAR; PG8_WAIT_L(0); PG8_MMA(1, 0, At, B0); PG8_BAR; PG8_SCHED;
	s_add_u32 s48, s52, 0x80000
	s_addc_u32 s49, s53, 0
	s_add_i32 s66, s67, s28
	v_lshl_add_u64 v[154:155], s[48:49], 0, v[0:1]
	s_mov_b32 m0, s66
	s_nop 0
	global_load_lds_dwordx4 v[154:155], off
	v_lshl_add_u64 v[154:155], s[48:49], 0, v[148:149]
	s_add_i32 m0, s66, 0x2000
	s_nop 0
	global_load_lds_dwordx4 v[154:155], off
	s_waitcnt vmcnt(6)
	s_barrier
	s_setprio 1
	v_mfma_f32_16x16x32_bf16 v[54:57], v[228:231], v[196:199], v[54:57]
	v_mfma_f32_16x16x32_bf16 v[50:53], v[236:239], v[196:199], v[50:53]
	v_mfma_f32_16x16x32_bf16 v[38:41], v[228:231], v[204:207], v[38:41]
	v_mfma_f32_16x16x32_bf16 v[34:37], v[236:239], v[204:207], v[34:37]
	v_mfma_f32_16x16x32_bf16 v[22:25], v[228:231], v[212:215], v[22:25]
	v_mfma_f32_16x16x32_bf16 v[18:21], v[236:239], v[212:215], v[18:21]
	v_mfma_f32_16x16x32_bf16 v[6:9], v[228:231], v[220:223], v[6:9]
	v_mfma_f32_16x16x32_bf16 v[2:5], v[236:239], v[220:223], v[2:5]
	v_mfma_f32_16x16x32_bf16 v[54:57], v[232:235], v[200:203], v[54:57]
	v_mfma_f32_16x16x32_bf16 v[50:53], v[240:243], v[200:203], v[50:53]
	v_mfma_f32_16x16x32_bf16 v[38:41], v[232:235], v[208:211], v[38:41]
	v_mfma_f32_16x16x32_bf16 v[34:37], v[240:243], v[208:211], v[34:37]
	v_mfma_f32_16x16x32_bf16 v[22:25], v[232:235], v[216:219], v[22:25]
	v_mfma_f32_16x16x32_bf16 v[18:21], v[240:243], v[216:219], v[18:21]
	v_mfma_f32_16x16x32_bf16 v[6:9], v[232:235], v[224:227], v[6:9]
	v_mfma_f32_16x16x32_bf16 v[2:5], v[240:243], v[224:227], v[2:5]
	s_setprio 0
	s_add_i32 s66, 0, 0x18000
	v_add_u32_e32 v163, s66, v160
	s_barrier
	ds_read_b128 v[154:157], v163
	ds_read_b128 v[164:167], v163 offset:1024
	ds_read_b128 v[188:191], v163 offset:2048
	ds_read_b128 v[192:195], v163 offset:3072
	s_add_u32 s48, s54, 0x80000
	s_addc_u32 s49, s55, 0
	s_mov_b32 m0, s58
	v_lshl_add_u64 v[228:229], s[48:49], 0, v[0:1]
	ds_read_b128 v[196:199], v162 offset:32768
	ds_read_b128 v[200:203], v162 offset:33792
	ds_read_b128 v[204:207], v162 offset:34816
	ds_read_b128 v[208:211], v162 offset:35840
	ds_read_b128 v[212:215], v162 offset:36864
	ds_read_b128 v[216:219], v162 offset:37888
	ds_read_b128 v[220:223], v162 offset:38912
	ds_read_b128 v[224:227], v162 offset:39936
	global_load_lds_dwordx4 v[228:229], off
	v_lshl_add_u64 v[228:229], s[48:49], 0, v[148:149]
	s_mov_b32 m0, s59
	s_nop 0
	global_load_lds_dwordx4 v[228:229], off
	s_waitcnt lgkmcnt(8)
	s_barrier
	s_waitcnt lgkmcnt(0)
	s_setprio 1
	s_waitcnt lgkmcnt(0)
	v_mfma_f32_16x16x32_bf16 v[126:129], v[154:157], v[196:199], v[126:129]
	v_mfma_f32_16x16x32_bf16 v[122:125], v[188:191], v[196:199], v[122:125]
	v_mfma_f32_16x16x32_bf16 v[110:113], v[154:157], v[204:207], v[110:113]
	v_mfma_f32_16x16x32_bf16 v[106:109], v[188:191], v[204:207], v[106:109]
	v_mfma_f32_16x16x32_bf16 v[94:97], v[154:157], v[212:215], v[94:97]
	v_mfma_f32_16x16x32_bf16 v[90:93], v[188:191], v[212:215], v[90:93]
	v_mfma_f32_16x16x32_bf16 v[78:81], v[154:157], v[220:223], v[78:81]
	v_mfma_f32_16x16x32_bf16 v[74:77], v[188:191], v[220:223], v[74:77]
	v_mfma_f32_16x16x32_bf16 v[126:129], v[164:167], v[200:203], v[126:129]
	v_mfma_f32_16x16x32_bf16 v[122:125], v[192:195], v[200:203], v[122:125]
	v_mfma_f32_16x16x32_bf16 v[110:113], v[164:167], v[208:211], v[110:113]
	v_mfma_f32_16x16x32_bf16 v[106:109], v[192:195], v[208:211], v[106:109]
	v_mfma_f32_16x16x32_bf16 v[94:97], v[164:167], v[216:219], v[94:97]
	v_mfma_f32_16x16x32_bf16 v[90:93], v[192:195], v[216:219], v[90:93]
	v_mfma_f32_16x16x32_bf16 v[78:81], v[164:167], v[224:227], v[78:81]
	v_mfma_f32_16x16x32_bf16 v[74:77], v[192:195], v[224:227], v[74:77]
	s_setprio 0
	s_barrier
	s_add_i32 s54, 0, 0x1c000
	s_add_i32 s48, s66, s28
	v_add_u32_e32 v163, s54, v160
	v_lshl_add_u64 v[158:159], v[158:159], 0, s[4:5]
	s_mov_b32 m0, s48
	ds_read_b128 v[228:231], v163
	ds_read_b128 v[232:235], v163 offset:1024
	ds_read_b128 v[236:239], v163 offset:2048
	ds_read_b128 v[240:243], v163 offset:3072
	global_load_lds_dwordx4 v[158:159], off
	v_lshl_add_u64 v[158:159], v[178:179], 0, s[4:5]
	s_add_i32 m0, s48, 0x2000
	s_nop 0
	global_load_lds_dwordx4 v[158:159], off
	s_barrier
; #define PG8_STAGE(bufoff, gbase, voff) do { _Pragma("unroll") for (int _i = 0; _i < 2; ++_i) \
;     __builtin_amdgcn_global_load_lds((const unsigned*)((const char*)(gbase) + (voff)[_i]), (PG8_LAS unsigned*)(lds + (bufoff) + ldsw + _i * 8192), 16, 0, 0); } while (0)
; #define PG8_LDA(dst, b, h) do { _Pragma("unroll") for (int m = 0; m < 4; ++m) _Pragma("unroll") for (int k = 0; k < 2; ++k) dst[m][k] = *(const PG8_LAS bf16x8*)(lds + PG8_SA(b, h) + aoff + m * 2048 + k * 1024); } while (0)
; #define PG8_MMA(ai, bj, At, Bt) do { __builtin_amdgcn_s_setprio(1); _Pragma("unroll") for (int m = 0; m < 4; ++m) _Pragma("unroll") for (int n = 0; n < 2; ++n) _Pragma("unroll") for (int k = 0; k < 2; ++k) \
;     acc[ai][bj][m][n] = __builtin_amdgcn_mfma_f32_16x16x32_bf16(Bt[n][k], At[m][k], acc[ai][bj][m][n], 0, 0, 0); __builtin_amdgcn_s_setprio(0); } while (0)
; #define PG8_WAIT_V(n) asm volatile("s_waitcnt vmcnt(" #n ")" ::: "memory")
; #define PG8_WAIT_L(n) asm volatile("s_waitcnt lgkmcnt(" #n ")" ::: "memory")
; #define PG8_BAR __builtin_amdgcn_s_barrier()
; #define PG8_SCHED __builtin_amdgcn_sched_barrier(0)
; template <class Epi>
; __device__ __forceinline__ void gemm_phase(PG8_LAS unsigned char* lds, const Gemm g, const StaticOrder& S, const Epi& E) {
;     ...
;       PG8_BAR; PG8_WAIT_L(0); PG8_MMA(0, 1, At, B1); PG8_BAR;
;       PG8_LDA(At, 1, 1); PG8_STAGE(PG8_SA(1, 0), a3, voffA);
;       PG8_BAR; PG8_WAIT_L(0); PG8_MMA(1, 0, At, B0); PG8_BAR; PG8_SCHED;
;       PG8_STAGE(PG8_SB(1, 1), b3 + hstep, voffB);
;       PG8_WAIT_V(6); PG8_BAR; PG8_MMA(1, 1, At, B1); PG8_BAR;
	s_waitcnt lgkmcnt(0)
	s_setprio 1
	s_waitcnt lgkmcnt(0)
	v_mfma_f32_16x16x32_bf16 v[118:121], v[228:231], v[196:199], v[118:121]
	v_mfma_f32_16x16x32_bf16 v[114:117], v[236:239], v[196:199], v[114:117]
	v_mfma_f32_16x16x32_bf16 v[102:105], v[228:231], v[204:207], v[102:105]
	v_mfma_f32_16x16x32_bf16 v[98:101], v[236:239], v[204:207], v[98:101]
	v_mfma_f32_16x16x32_bf16 v[86:89], v[228:231], v[212:215], v[86:89]
	v_mfma_f32_16x16x32_bf16 v[82:85], v[236:239], v[212:215], v[82:85]
	v_mfma_f32_16x16x32_bf16 v[70:73], v[228:231], v[220:223], v[70:73]
	v_mfma_f32_16x16x32_bf16 v[66:69], v[236:239], v[220:223], v[66:69]
	v_mfma_f32_16x16x32_bf16 v[118:121], v[232:235], v[200:203], v[118:121]
	v_mfma_f32_16x16x32_bf16 v[114:117], v[240:243], v[200:203], v[114:117]
	v_mfma_f32_16x16x32_bf16 v[102:105], v[232:235], v[208:211], v[102:105]
	v_mfma_f32_16x16x32_bf16 v[98:101], v[240:243], v[208:211], v[98:101]
	v_mfma_f32_16x16x32_bf16 v[86:89], v[232:235], v[216:219], v[86:89]
	v_mfma_f32_16x16x32_bf16 v[82:85], v[240:243], v[216:219], v[82:85]
	v_mfma_f32_16x16x32_bf16 v[70:73], v[232:235], v[224:227], v[70:73]
	v_mfma_f32_16x16x32_bf16 v[66:69], v[240:243], v[224:227], v[66:69]
	s_setprio 0
	s_mov_b32 m0, s60
	v_lshl_add_u64 v[158:159], v[244:245], 0, s[4:5]
	s_barrier
	ds_read_b128 v[196:199], v162 offset:49152
	ds_read_b128 v[200:203], v162 offset:50176
	ds_read_b128 v[204:207], v162 offset:51200
	ds_read_b128 v[208:211], v162 offset:52224
	ds_read_b128 v[212:215], v162 offset:53248
	ds_read_b128 v[216:219], v162 offset:54272
	ds_read_b128 v[220:223], v162 offset:55296
	ds_read_b128 v[224:227], v162 offset:56320
	global_load_lds_dwordx4 v[158:159], off
	v_lshl_add_u64 v[158:159], v[246:247], 0, s[4:5]
	s_mov_b32 m0, s61
	s_nop 0
	global_load_lds_dwordx4 v[158:159], off
	s_barrier
	s_waitcnt lgkmcnt(0)
	s_setprio 1
	s_waitcnt lgkmcnt(0)
	v_mfma_f32_16x16x32_bf16 v[62:65], v[154:157], v[196:199], v[62:65]
	v_mfma_f32_16x16x32_bf16 v[58:61], v[188:191], v[196:199], v[58:61]
	v_mfma_f32_16x16x32_bf16 v[46:49], v[154:157], v[204:207], v[46:49]
	v_mfma_f32_16x16x32_bf16 v[42:45], v[188:191], v[204:207], v[42:45]
	v_mfma_f32_16x16x32_bf16 v[30:33], v[154:157], v[212:215], v[30:33]
	v_mfma_f32_16x16x32_bf16 v[26:29], v[188:191], v[212:215], v[26:29]
	v_mfma_f32_16x16x32_bf16 v[14:17], v[154:157], v[220:223], v[14:17]
	v_mfma_f32_16x16x32_bf16 v[10:13], v[188:191], v[220:223], v[10:13]
	v_mfma_f32_16x16x32_bf16 v[62:65], v[164:167], v[200:203], v[62:65]
	v_mfma_f32_16x16x32_bf16 v[58:61], v[192:195], v[200:203], v[58:61]
	v_mfma_f32_16x16x32_bf16 v[46:49], v[164:167], v[208:211], v[46:49]
	v_mfma_f32_16x16x32_bf16 v[42:45], v[192:195], v[208:211], v[42:45]
	v_mfma_f32_16x16x32_bf16 v[30:33], v[164:167], v[216:219], v[30:33]
	v_mfma_f32_16x16x32_bf16 v[26:29], v[192:195], v[216:219], v[26:29]
	v_mfma_f32_16x16x32_bf16 v[14:17], v[164:167], v[224:227], v[14:17]
	v_mfma_f32_16x16x32_bf16 v[10:13], v[192:195], v[224:227], v[10:13]
	s_setprio 0
	s_barrier
	s_add_u32 s48, s52, 0x80080
	s_addc_u32 s49, s53, 0
	s_add_i32 s52, s54, s28
	v_lshl_add_u64 v[154:155], s[48:49], 0, v[0:1]
	s_mov_b32 m0, s52
	s_nop 0
	global_load_lds_dwordx4 v[154:155], off
	v_lshl_add_u64 v[154:155], s[48:49], 0, v[148:149]
	s_add_i32 m0, s52, 0x2000
	s_nop 0
	global_load_lds_dwordx4 v[154:155], off
	s_waitcnt vmcnt(6)
	s_barrier
	s_setprio 1
	v_mfma_f32_16x16x32_bf16 v[54:57], v[228:231], v[196:199], v[54:57]
	v_mfma_f32_16x16x32_bf16 v[50:53], v[236:239], v[196:199], v[50:53]
	v_mfma_f32_16x16x32_bf16 v[38:41], v[228:231], v[204:207], v[38:41]
	v_mfma_f32_16x16x32_bf16 v[34:37], v[236:239], v[204:207], v[34:37]
	v_mfma_f32_16x16x32_bf16 v[22:25], v[228:231], v[212:215], v[22:25]
	v_mfma_f32_16x16x32_bf16 v[18:21], v[236:239], v[212:215], v[18:21]
	v_mfma_f32_16x16x32_bf16 v[6:9], v[228:231], v[220:223], v[6:9]
	v_mfma_f32_16x16x32_bf16 v[2:5], v[236:239], v[220:223], v[2:5]
	v_mfma_f32_16x16x32_bf16 v[54:57], v[232:235], v[200:203], v[54:57]
	v_mfma_f32_16x16x32_bf16 v[50:53], v[240:243], v[200:203], v[50:53]
	v_mfma_f32_16x16x32_bf16 v[38:41], v[232:235], v[208:211], v[38:41]
	v_mfma_f32_16x16x32_bf16 v[34:37], v[240:243], v[208:211], v[34:37]
	v_mfma_f32_16x16x32_bf16 v[22:25], v[232:235], v[216:219], v[22:25]
	v_mfma_f32_16x16x32_bf16 v[18:21], v[240:243], v[216:219], v[18:21]
	v_mfma_f32_16x16x32_bf16 v[6:9], v[232:235], v[224:227], v[6:9]
	v_mfma_f32_16x16x32_bf16 v[2:5], v[240:243], v[224:227], v[2:5]
	s_setprio 0
	s_add_i32 s65, s65, 2
	s_add_u32 s63, s63, 0x100
	s_addc_u32 s64, s64, 0
	s_cmp_gt_u32 s65, 29
	s_mov_b64 s[48:49], s[50:51]
	s_barrier
	s_cbranch_scc0 .LBB0_1046
	v_readlane_b32 s80, v254, 5
	v_readlane_b32 s81, v254, 6
	v_readlane_b32 s82, v254, 7
	v_readlane_b32 s83, v254, 8
	s_cmp_ge_i32 s46, 65
	s_cselect_b32 s68, 1, 0
	s_mul_i32 s69, s68, 65
	s_sub_i32 s69, s46, s69
	s_cmp_eq_u32 s69, 0
	s_cbranch_scc1 .LepiB_ctx
	s_add_i32 s69, s69, -1
	s_lshl_b32 s69, s69, 8
	s_lshl_b32 s70, s68, 14
	s_add_i32 s69, s69, s70
	s_lshl_b32 s69, s69, 12
	s_add_u32 s70, s80, s69
	s_addc_u32 s71, s81, 0
	s_mul_i32 s68, s68, 0x3000
	s_branch .LepiB_go

; #define PG8_STAGE(bufoff, gbase, voff) do { _Pragma("unroll") for (int _i = 0; _i < 2; ++_i) \
;     __builtin_amdgcn_global_load_lds((const unsigned*)((const char*)(gbase) + (voff)[_i]), (PG8_LAS unsigned*)(lds + (bufoff) + ldsw + _i * 8192), 16, 0, 0); } while (0)
; #define PG8_LDA(dst, b, h) do { _Pragma("unroll") for (int m = 0; m < 4; ++m) _Pragma("unroll") for (int k = 0; k < 2; ++k) dst[m][k] = *(const PG8_LAS bf16x8*)(lds + PG8_SA(b, h) + aoff + m * 2048 + k * 1024); } while (0)
; #define PG8_LDB(dst, b, h) do { _Pragma("unroll") for (int n = 0; n < 2; ++n) _Pragma("unroll") for (int k = 0; k < 2; ++k) dst[n][k] = *(const PG8_LAS bf16x8*)(lds + PG8_SB(b, h) + boff + n * 2048 + k * 1024); } while (0)
; #define PG8_MMA(ai, bj, At, Bt) do { __builtin_amdgcn_s_setprio(1); _Pragma("unroll") for (int m = 0; m < 4; ++m) _Pragma("unroll") for (int n = 0; n < 2; ++n) _Pragma("unroll") for (int k = 0; k < 2; ++k) \
;     acc[ai][bj][m][n] = __builtin_amdgcn_mfma_f32_16x16x32_bf16(Bt[n][k], At[m][k], acc[ai][bj][m][n], 0, 0, 0); __builtin_amdgcn_s_setprio(0); } while (0)
; #define PG8_WAIT_V(n) asm volatile("s_waitcnt vmcnt(" #n ")" ::: "memory")
; #define PG8_WAIT_L(n) asm volatile("s_waitcnt lgkmcnt(" #n ")" ::: "memory")
; #define PG8_BAR __builtin_amdgcn_s_barrier()
; #define PG8_SCHED __builtin_amdgcn_sched_barrier(0)
; template <class Epi>
; __device__ __forceinline__ void gemm_phase(PG8_LAS unsigned char* lds, const Gemm g, const StaticOrder& S, const Epi& E) {
;     ...
;       PG8_LDB(B0, 0, 0); PG8_SCHED; PG8_LDA(At, 0, 0); PG8_STAGE(PG8_SA(1, 1), a1 + hstep, voffA);
;       PG8_WAIT_L(8); PG8_BAR; PG8_WAIT_L(0); PG8_MMA(0, 0, At, B0); PG8_BAR; PG8_SCHED;
;       PG8_LDB(B1, 0, 1); PG8_STAGE(PG8_SB(0, 0), b2, voffB);
;       PG8_BAR; PG8_WAIT_L(0); PG8_MMA(0, 1, At, B1); PG8_BAR;
;       PG8_LDA(At, 0, 1); PG8_STAGE(PG8_SA(0, 0), a2, voffA);
;       PG8_BAR; PG8_WAIT_L(0); PG8_MMA(1, 0, At, B0); PG8_BAR; PG8_SCHED;
;       PG8_STAGE(PG8_SB(0, 1), b2 + hstep, voffB);
;       PG8_WAIT_V(6); PG8_BAR; PG8_MMA(1, 1, At, B1); PG8_BAR;
.LBB0_1410:
	s_add_u32 s42, s30, 0x100
	s_addc_u32 s43, s31, 0
	s_add_i32 s62, 0, 0x10000
	v_add_u32_e32 v158, s62, v160
	ds_read_b128 v[154:157], v158
	ds_read_b128 v[164:167], v158 offset:1024
	ds_read_b128 v[188:191], v158 offset:2048
	ds_read_b128 v[192:195], v158 offset:3072
	s_cmp_eq_u32 s61, 16
	s_cselect_b32 s47, s9, s43
	s_cselect_b32 s46, s8, s42
	s_cselect_b32 s45, s11, s60
	s_cselect_b32 s44, s10, s59
	v_lshl_add_u64 v[158:159], s[30:31], 0, v[150:151]
	s_add_i32 m0, s48, 0xc000
	ds_read_b128 v[196:199], v162
	ds_read_b128 v[200:203], v162 offset:1024
	ds_read_b128 v[204:207], v162 offset:2048
	ds_read_b128 v[208:211], v162 offset:3072
	ds_read_b128 v[212:215], v162 offset:4096
	ds_read_b128 v[216:219], v162 offset:5120
	ds_read_b128 v[220:223], v162 offset:6144
	ds_read_b128 v[224:227], v162 offset:7168
	global_load_lds_dwordx4 v[158:159], off
	v_lshl_add_u64 v[158:159], s[30:31], 0, v[152:153]
	s_add_i32 m0, s48, 0xe000
	s_nop 0
	global_load_lds_dwordx4 v[158:159], off
	s_waitcnt lgkmcnt(8)
	s_barrier
	s_waitcnt lgkmcnt(0)
	s_setprio 1
	s_waitcnt lgkmcnt(0)
	v_mfma_f32_16x16x32_bf16 v[126:129], v[154:157], v[196:199], v[126:129]
	v_mfma_f32_16x16x32_bf16 v[122:125], v[188:191], v[196:199], v[122:125]
	v_mfma_f32_16x16x32_bf16 v[110:113], v[154:157], v[204:207], v[110:113]
	v_mfma_f32_16x16x32_bf16 v[106:109], v[188:191], v[204:207], v[106:109]
	v_mfma_f32_16x16x32_bf16 v[94:97], v[154:157], v[212:215], v[94:97]
	v_mfma_f32_16x16x32_bf16 v[90:93], v[188:191], v[212:215], v[90:93]
	v_mfma_f32_16x16x32_bf16 v[78:81], v[154:157], v[220:223], v[78:81]
	v_mfma_f32_16x16x32_bf16 v[74:77], v[188:191], v[220:223], v[74:77]
	v_mfma_f32_16x16x32_bf16 v[126:129], v[164:167], v[200:203], v[126:129]
	v_mfma_f32_16x16x32_bf16 v[122:125], v[192:195], v[200:203], v[122:125]
	v_mfma_f32_16x16x32_bf16 v[110:113], v[164:167], v[208:211], v[110:113]
	v_mfma_f32_16x16x32_bf16 v[106:109], v[192:195], v[208:211], v[106:109]
	v_mfma_f32_16x16x32_bf16 v[94:97], v[164:167], v[216:219], v[94:97]
	v_mfma_f32_16x16x32_bf16 v[90:93], v[192:195], v[216:219], v[90:93]
	v_mfma_f32_16x16x32_bf16 v[78:81], v[164:167], v[224:227], v[78:81]
	v_mfma_f32_16x16x32_bf16 v[74:77], v[192:195], v[224:227], v[74:77]
	s_setprio 0
	s_barrier
	s_add_i32 s63, 0, 0x14000
	v_add_u32_e32 v158, s63, v160
	s_add_i32 s30, s62, s28
	ds_read_b128 v[228:231], v158
	ds_read_b128 v[232:235], v158 offset:1024
	ds_read_b128 v[236:239], v158 offset:2048
	ds_read_b128 v[240:243], v158 offset:3072
	v_lshl_add_u64 v[158:159], s[44:45], 0, v[0:1]
	s_mov_b32 m0, s30
	v_lshl_add_u64 v[178:179], s[44:45], 0, v[148:149]
	global_load_lds_dwordx4 v[158:159], off
	s_add_i32 m0, s30, 0x2000
	s_nop 0
	global_load_lds_dwordx4 v[178:179], off
	s_barrier
	s_waitcnt lgkmcnt(0)
	s_setprio 1
	s_waitcnt lgkmcnt(0)
	v_mfma_f32_16x16x32_bf16 v[118:121], v[228:231], v[196:199], v[118:121]
	v_mfma_f32_16x16x32_bf16 v[114:117], v[236:239], v[196:199], v[114:117]
	v_mfma_f32_16x16x32_bf16 v[102:105], v[228:231], v[204:207], v[102:105]
	v_mfma_f32_16x16x32_bf16 v[98:101], v[236:239], v[204:207], v[98:101]
	v_mfma_f32_16x16x32_bf16 v[86:89], v[228:231], v[212:215], v[86:89]
	v_mfma_f32_16x16x32_bf16 v[82:85], v[236:239], v[212:215], v[82:85]
	v_mfma_f32_16x16x32_bf16 v[70:73], v[228:231], v[220:223], v[70:73]
	v_mfma_f32_16x16x32_bf16 v[66:69], v[236:239], v[220:223], v[66:69]
	v_mfma_f32_16x16x32_bf16 v[118:121], v[232:235], v[200:203], v[118:121]
	v_mfma_f32_16x16x32_bf16 v[114:117], v[240:243], v[200:203], v[114:117]
	v_mfma_f32_16x16x32_bf16 v[102:105], v[232:235], v[208:211], v[102:105]
	v_mfma_f32_16x16x32_bf16 v[98:101], v[240:243], v[208:211], v[98:101]
	v_mfma_f32_16x16x32_bf16 v[86:89], v[232:235], v[216:219], v[86:89]
	v_mfma_f32_16x16x32_bf16 v[82:85], v[240:243], v[216:219], v[82:85]
	v_mfma_f32_16x16x32_bf16 v[70:73], v[232:235], v[224:227], v[70:73]
	v_mfma_f32_16x16x32_bf16 v[66:69], v[240:243], v[224:227], v[66:69]
	s_setprio 0
	s_mov_b32 m0, s48
	v_lshl_add_u64 v[244:245], s[46:47], 0, v[0:1]
	s_barrier
	ds_read_b128 v[196:199], v162 offset:16384
	ds_read_b128 v[200:203], v162 offset:17408
	ds_read_b128 v[204:207], v162 offset:18432
	ds_read_b128 v[208:211], v162 offset:19456
	ds_read_b128 v[212:215], v162 offset:20480
	ds_read_b128 v[216:219], v162 offset:21504
	ds_read_b128 v[220:223], v162 offset:22528
	ds_read_b128 v[224:227], v162 offset:23552
	global_load_lds_dwordx4 v[244:245], off
	v_lshl_add_u64 v[246:247], s[46:47], 0, v[148:149]
	s_mov_b32 m0, s49
	s_nop 0
	global_load_lds_dwordx4 v[246:247], off
	s_barrier
	s_waitcnt lgkmcnt(0)
	s_setprio 1
	s_waitcnt lgkmcnt(0)
	v_mfma_f32_16x16x32_bf16 v[62:65], v[154:157], v[196:199], v[62:65]
	v_mfma_f32_16x16x32_bf16 v[58:61], v[188:191], v[196:199], v[58:61]
	v_mfma_f32_16x16x32_bf16 v[46:49], v[154:157], v[204:207], v[46:49]
	v_mfma_f32_16x16x32_bf16 v[42:45], v[188:191], v[204:207], v[42:45]
	v_mfma_f32_16x16x32_bf16 v[30:33], v[154:157], v[212:215], v[30:33]
	v_mfma_f32_16x16x32_bf16 v[26:29], v[188:191], v[212:215], v[26:29]
	v_mfma_f32_16x16x32_bf16 v[14:17], v[154:157], v[220:223], v[14:17]
	v_mfma_f32_16x16x32_bf16 v[10:13], v[188:191], v[220:223], v[10:13]
	v_mfma_f32_16x16x32_bf16 v[62:65], v[164:167], v[200:203], v[62:65]
	v_mfma_f32_16x16x32_bf16 v[58:61], v[192:195], v[200:203], v[58:61]
	v_mfma_f32_16x16x32_bf16 v[46:49], v[164:167], v[208:211], v[46:49]
	v_mfma_f32_16x16x32_bf16 v[42:45], v[192:195], v[208:211], v[42:45]
	v_mfma_f32_16x16x32_bf16 v[30:33], v[164:167], v[216:219], v[30:33]
	v_mfma_f32_16x16x32_bf16 v[26:29], v[192:195], v[216:219], v[26:29]
	v_mfma_f32_16x16x32_bf16 v[14:17], v[164:167], v[224:227], v[14:17]
	v_mfma_f32_16x16x32_bf16 v[10:13], v[192:195], v[224:227], v[10:13]
	s_setprio 0
	s_barrier
; #define PG8_STAGE(bufoff, gbase, voff) do { _Pragma("unroll") for (int _i = 0; _i < 2; ++_i) \
;     __builtin_amdgcn_global_load_lds((const unsigned*)((const char*)(gbase) + (voff)[_i]), (PG8_LAS unsigned*)(lds + (bufoff) + ldsw + _i * 8192), 16, 0, 0); } while (0)
; #define PG8_LDA(dst, b, h) do { _Pragma("unroll") for (int m = 0; m < 4; ++m) _Pragma("unroll") for (int k = 0; k < 2; ++k) dst[m][k] = *(const PG8_LAS bf16x8*)(lds + PG8_SA(b, h) + aoff + m * 2048 + k * 1024); } while (0)
; #define PG8_LDB(dst, b, h) do { _Pragma("unroll") for (int n = 0; n < 2; ++n) _Pragma("unroll") for (int k = 0; k < 2; ++k) dst[n][k] = *(const PG8_LAS bf16x8*)(lds + PG8_SB(b, h) + boff + n * 2048 + k * 1024); } while (0)
; #define PG8_MMA(ai, bj, At, Bt) do { __builtin_amdgcn_s_setprio(1); _Pragma("unroll") for (int m = 0; m < 4; ++m) _Pragma("unroll") for (int n = 0; n < 2; ++n) _Pragma("unroll") for (int k = 0; k < 2; ++k) \
;     acc[ai][bj][m][n] = __builtin_amdgcn_mfma_f32_16x16x32_bf16(Bt[n][k], At[m][k], acc[ai][bj][m][n], 0, 0, 0); __builtin_amdgcn_s_setprio(0); } while (0)
; #define PG8_WAIT_V(n) asm volatile("s_waitcnt vmcnt(" #n ")" ::: "memory")
; #define PG8_WAIT_L(n) asm volatile("s_waitcnt lgkmcnt(" #n ")" ::: "memory")
; #define PG8_BAR __builtin_amdgcn_s_barrier()
; #define PG8_SCHED __builtin_amdgcn_sched_barrier(0)
; template <class Epi>
; __device__ __forceinline__ void gemm_phase(PG8_LAS unsigned char* lds, const Gemm g, const StaticOrder& S, const Epi& E) {
;     ...
;       PG8_WAIT_V(6); PG8_BAR; PG8_MMA(1, 1, At, B1); PG8_BAR;
;       PG8_LDB(B0, 1, 0); PG8_SCHED; PG8_LDA(At, 1, 0); PG8_STAGE(PG8_SA(0, 1), a2 + hstep, voffA);
;       PG8_WAIT_L(8); PG8_BAR; PG8_WAIT_L(0); PG8_MMA(0, 0, At, B0); PG8_BAR; PG8_SCHED;
;       PG8_LDB(B1, 1, 1); PG8_STAGE(PG8_SB(1, 0), b3, voffB);
;       PG8_BAR; PG8_WAIT_L(0); PG8_MMA(0, 1, At, B1); PG8_BAR;
;       PG8_LDA(At, 1, 1); PG8_STAGE(PG8_SA(1, 0), a3, voffA);
;       PG8_BAR; PG8_WAIT_L(0); PG8_MMA(1, 0, At, B0); PG8_BAR; PG8_SCHED;
	s_add_u32 s30, s44, 0x50000
	s_addc_u32 s31, s45, 0
	s_add_i32 s62, s63, s28
	v_lshl_add_u64 v[154:155], s[30:31], 0, v[0:1]
	s_mov_b32 m0, s62
	s_nop 0
	global_load_lds_dwordx4 v[154:155], off
	v_lshl_add_u64 v[154:155], s[30:31], 0, v[148:149]
	s_add_i32 m0, s62, 0x2000
	s_nop 0
	global_load_lds_dwordx4 v[154:155], off
	s_waitcnt vmcnt(6)
	s_barrier
	s_setprio 1
	v_mfma_f32_16x16x32_bf16 v[54:57], v[228:231], v[196:199], v[54:57]
	v_mfma_f32_16x16x32_bf16 v[50:53], v[236:239], v[196:199], v[50:53]
	v_mfma_f32_16x16x32_bf16 v[38:41], v[228:231], v[204:207], v[38:41]
	v_mfma_f32_16x16x32_bf16 v[34:37], v[236:239], v[204:207], v[34:37]
	v_mfma_f32_16x16x32_bf16 v[22:25], v[228:231], v[212:215], v[22:25]
	v_mfma_f32_16x16x32_bf16 v[18:21], v[236:239], v[212:215], v[18:21]
	v_mfma_f32_16x16x32_bf16 v[6:9], v[228:231], v[220:223], v[6:9]
	v_mfma_f32_16x16x32_bf16 v[2:5], v[236:239], v[220:223], v[2:5]
	v_mfma_f32_16x16x32_bf16 v[54:57], v[232:235], v[200:203], v[54:57]
	v_mfma_f32_16x16x32_bf16 v[50:53], v[240:243], v[200:203], v[50:53]
	v_mfma_f32_16x16x32_bf16 v[38:41], v[232:235], v[208:211], v[38:41]
	v_mfma_f32_16x16x32_bf16 v[34:37], v[240:243], v[208:211], v[34:37]
	v_mfma_f32_16x16x32_bf16 v[22:25], v[232:235], v[216:219], v[22:25]
	v_mfma_f32_16x16x32_bf16 v[18:21], v[240:243], v[216:219], v[18:21]
	v_mfma_f32_16x16x32_bf16 v[6:9], v[232:235], v[224:227], v[6:9]
	v_mfma_f32_16x16x32_bf16 v[2:5], v[240:243], v[224:227], v[2:5]
	s_setprio 0
	s_add_i32 s62, 0, 0x18000
	v_add_u32_e32 v163, s62, v160
	s_barrier
	ds_read_b128 v[154:157], v163
	ds_read_b128 v[164:167], v163 offset:1024
	ds_read_b128 v[188:191], v163 offset:2048
	ds_read_b128 v[192:195], v163 offset:3072
	s_add_u32 s30, s46, 0x50000
	s_addc_u32 s31, s47, 0
	s_mov_b32 m0, s50
	v_lshl_add_u64 v[228:229], s[30:31], 0, v[0:1]
	ds_read_b128 v[196:199], v162 offset:32768
	ds_read_b128 v[200:203], v162 offset:33792
	ds_read_b128 v[204:207], v162 offset:34816
	ds_read_b128 v[208:211], v162 offset:35840
	ds_read_b128 v[212:215], v162 offset:36864
	ds_read_b128 v[216:219], v162 offset:37888
	ds_read_b128 v[220:223], v162 offset:38912
	ds_read_b128 v[224:227], v162 offset:39936
	global_load_lds_dwordx4 v[228:229], off
	v_lshl_add_u64 v[228:229], s[30:31], 0, v[148:149]
	s_mov_b32 m0, s51
	s_nop 0
	global_load_lds_dwordx4 v[228:229], off
	s_waitcnt lgkmcnt(8)
	s_barrier
	s_waitcnt lgkmcnt(0)
	s_setprio 1
	s_waitcnt lgkmcnt(0)
	v_mfma_f32_16x16x32_bf16 v[126:129], v[154:157], v[196:199], v[126:129]
	v_mfma_f32_16x16x32_bf16 v[122:125], v[188:191], v[196:199], v[122:125]
	v_mfma_f32_16x16x32_bf16 v[110:113], v[154:157], v[204:207], v[110:113]
	v_mfma_f32_16x16x32_bf16 v[106:109], v[188:191], v[204:207], v[106:109]
	v_mfma_f32_16x16x32_bf16 v[94:97], v[154:157], v[212:215], v[94:97]
	v_mfma_f32_16x16x32_bf16 v[90:93], v[188:191], v[212:215], v[90:93]
	v_mfma_f32_16x16x32_bf16 v[78:81], v[154:157], v[220:223], v[78:81]
	v_mfma_f32_16x16x32_bf16 v[74:77], v[188:191], v[220:223], v[74:77]
	v_mfma_f32_16x16x32_bf16 v[126:129], v[164:167], v[200:203], v[126:129]
	v_mfma_f32_16x16x32_bf16 v[122:125], v[192:195], v[200:203], v[122:125]
	v_mfma_f32_16x16x32_bf16 v[110:113], v[164:167], v[208:211], v[110:113]
	v_mfma_f32_16x16x32_bf16 v[106:109], v[192:195], v[208:211], v[106:109]
	v_mfma_f32_16x16x32_bf16 v[94:97], v[164:167], v[216:219], v[94:97]
	v_mfma_f32_16x16x32_bf16 v[90:93], v[192:195], v[216:219], v[90:93]
	v_mfma_f32_16x16x32_bf16 v[78:81], v[164:167], v[224:227], v[78:81]
	v_mfma_f32_16x16x32_bf16 v[74:77], v[192:195], v[224:227], v[74:77]
	s_setprio 0
	s_barrier
	s_add_i32 s46, 0, 0x1c000
	s_add_i32 s30, s62, s28
	v_add_u32_e32 v163, s46, v160
	v_lshl_add_u64 v[158:159], v[158:159], 0, s[4:5]
	s_mov_b32 m0, s30
	ds_read_b128 v[228:231], v163
	ds_read_b128 v[232:235], v163 offset:1024
	ds_read_b128 v[236:239], v163 offset:2048
	ds_read_b128 v[240:243], v163 offset:3072
	global_load_lds_dwordx4 v[158:159], off
	v_lshl_add_u64 v[158:159], v[178:179], 0, s[4:5]
	s_add_i32 m0, s30, 0x2000
	s_nop 0
	global_load_lds_dwordx4 v[158:159], off
	s_barrier
; #define PG8_STAGE(bufoff, gbase, voff) do { _Pragma("unroll") for (int _i = 0; _i < 2; ++_i) \
;     __builtin_amdgcn_global_load_lds((const unsigned*)((const char*)(gbase) + (voff)[_i]), (PG8_LAS unsigned*)(lds + (bufoff) + ldsw + _i * 8192), 16, 0, 0); } while (0)
; #define PG8_LDA(dst, b, h) do { _Pragma("unroll") for (int m = 0; m < 4; ++m) _Pragma("unroll") for (int k = 0; k < 2; ++k) dst[m][k] = *(const PG8_LAS bf16x8*)(lds + PG8_SA(b, h) + aoff + m * 2048 + k * 1024); } while (0)
; #define PG8_MMA(ai, bj, At, Bt) do { __builtin_amdgcn_s_setprio(1); _Pragma("unroll") for (int m = 0; m < 4; ++m) _Pragma("unroll") for (int n = 0; n < 2; ++n) _Pragma("unroll") for (int k = 0; k < 2; ++k) \
;     acc[ai][bj][m][n] = __builtin_amdgcn_mfma_f32_16x16x32_bf16(Bt[n][k], At[m][k], acc[ai][bj][m][n], 0, 0, 0); __builtin_amdgcn_s_setprio(0); } while (0)
; #define PG8_WAIT_V(n) asm volatile("s_waitcnt vmcnt(" #n ")" ::: "memory")
; #define PG8_WAIT_L(n) asm volatile("s_waitcnt lgkmcnt(" #n ")" ::: "memory")
; #define PG8_BAR __builtin_amdgcn_s_barrier()
; #define PG8_SCHED __builtin_amdgcn_sched_barrier(0)
; template <class Epi>
; __device__ __forceinline__ void gemm_phase(PG8_LAS unsigned char* lds, const Gemm g, const StaticOrder& S, const Epi& E) {
;     ...
;       PG8_BAR; PG8_WAIT_L(0); PG8_MMA(0, 1, At, B1); PG8_BAR;
;       PG8_LDA(At, 1, 1); PG8_STAGE(PG8_SA(1, 0), a3, voffA);
;       PG8_BAR; PG8_WAIT_L(0); PG8_MMA(1, 0, At, B0); PG8_BAR; PG8_SCHED;
;       PG8_STAGE(PG8_SB(1, 1), b3 + hstep, voffB);
;       PG8_WAIT_V(6); PG8_BAR; PG8_MMA(1, 1, At, B1); PG8_BAR;
	s_waitcnt lgkmcnt(0)
	s_setprio 1
	s_waitcnt lgkmcnt(0)
	v_mfma_f32_16x16x32_bf16 v[118:121], v[228:231], v[196:199], v[118:121]
	v_mfma_f32_16x16x32_bf16 v[114:117], v[236:239], v[196:199], v[114:117]
	v_mfma_f32_16x16x32_bf16 v[102:105], v[228:231], v[204:207], v[102:105]
	v_mfma_f32_16x16x32_bf16 v[98:101], v[236:239], v[204:207], v[98:101]
	v_mfma_f32_16x16x32_bf16 v[86:89], v[228:231], v[212:215], v[86:89]
	v_mfma_f32_16x16x32_bf16 v[82:85], v[236:239], v[212:215], v[82:85]
	v_mfma_f32_16x16x32_bf16 v[70:73], v[228:231], v[220:223], v[70:73]
	v_mfma_f32_16x16x32_bf16 v[66:69], v[236:239], v[220:223], v[66:69]
	v_mfma_f32_16x16x32_bf16 v[118:121], v[232:235], v[200:203], v[118:121]
	v_mfma_f32_16x16x32_bf16 v[114:117], v[240:243], v[200:203], v[114:117]
	v_mfma_f32_16x16x32_bf16 v[102:105], v[232:235], v[208:211], v[102:105]
	v_mfma_f32_16x16x32_bf16 v[98:101], v[240:243], v[208:211], v[98:101]
	v_mfma_f32_16x16x32_bf16 v[86:89], v[232:235], v[216:219], v[86:89]
	v_mfma_f32_16x16x32_bf16 v[82:85], v[240:243], v[216:219], v[82:85]
	v_mfma_f32_16x16x32_bf16 v[70:73], v[232:235], v[224:227], v[70:73]
	v_mfma_f32_16x16x32_bf16 v[66:69], v[240:243], v[224:227], v[66:69]
	s_setprio 0
	s_mov_b32 m0, s52
	v_lshl_add_u64 v[158:159], v[244:245], 0, s[4:5]
	s_barrier
	ds_read_b128 v[196:199], v162 offset:49152
	ds_read_b128 v[200:203], v162 offset:50176
	ds_read_b128 v[204:207], v162 offset:51200
	ds_read_b128 v[208:211], v162 offset:52224
	ds_read_b128 v[212:215], v162 offset:53248
	ds_read_b128 v[216:219], v162 offset:54272
	ds_read_b128 v[220:223], v162 offset:55296
	ds_read_b128 v[224:227], v162 offset:56320
	global_load_lds_dwordx4 v[158:159], off
	v_lshl_add_u64 v[158:159], v[246:247], 0, s[4:5]
	s_mov_b32 m0, s53
	s_nop 0
	global_load_lds_dwordx4 v[158:159], off
	s_barrier
	s_waitcnt lgkmcnt(0)
	s_setprio 1
	s_waitcnt lgkmcnt(0)
	v_mfma_f32_16x16x32_bf16 v[62:65], v[154:157], v[196:199], v[62:65]
	v_mfma_f32_16x16x32_bf16 v[58:61], v[188:191], v[196:199], v[58:61]
	v_mfma_f32_16x16x32_bf16 v[46:49], v[154:157], v[204:207], v[46:49]
	v_mfma_f32_16x16x32_bf16 v[42:45], v[188:191], v[204:207], v[42:45]
	v_mfma_f32_16x16x32_bf16 v[30:33], v[154:157], v[212:215], v[30:33]
	v_mfma_f32_16x16x32_bf16 v[26:29], v[188:191], v[212:215], v[26:29]
	v_mfma_f32_16x16x32_bf16 v[14:17], v[154:157], v[220:223], v[14:17]
	v_mfma_f32_16x16x32_bf16 v[10:13], v[188:191], v[220:223], v[10:13]
	v_mfma_f32_16x16x32_bf16 v[62:65], v[164:167], v[200:203], v[62:65]
	v_mfma_f32_16x16x32_bf16 v[58:61], v[192:195], v[200:203], v[58:61]
	v_mfma_f32_16x16x32_bf16 v[46:49], v[164:167], v[208:211], v[46:49]
	v_mfma_f32_16x16x32_bf16 v[42:45], v[192:195], v[208:211], v[42:45]
	v_mfma_f32_16x16x32_bf16 v[30:33], v[164:167], v[216:219], v[30:33]
	v_mfma_f32_16x16x32_bf16 v[26:29], v[192:195], v[216:219], v[26:29]
	v_mfma_f32_16x16x32_bf16 v[14:17], v[164:167], v[224:227], v[14:17]
	v_mfma_f32_16x16x32_bf16 v[10:13], v[192:195], v[224:227], v[10:13]
	s_setprio 0
	s_barrier
	s_add_u32 s30, s44, 0x50080
	s_addc_u32 s31, s45, 0
	s_add_i32 s44, s46, s28
	v_lshl_add_u64 v[154:155], s[30:31], 0, v[0:1]
	s_mov_b32 m0, s44
	s_nop 0
	global_load_lds_dwordx4 v[154:155], off
	v_lshl_add_u64 v[154:155], s[30:31], 0, v[148:149]
	s_add_i32 m0, s44, 0x2000
	s_nop 0
	global_load_lds_dwordx4 v[154:155], off
	s_waitcnt vmcnt(6)
	s_barrier
	s_setprio 1
	v_mfma_f32_16x16x32_bf16 v[54:57], v[228:231], v[196:199], v[54:57]
	v_mfma_f32_16x16x32_bf16 v[50:53], v[236:239], v[196:199], v[50:53]
	v_mfma_f32_16x16x32_bf16 v[38:41], v[228:231], v[204:207], v[38:41]
	v_mfma_f32_16x16x32_bf16 v[34:37], v[236:239], v[204:207], v[34:37]
	v_mfma_f32_16x16x32_bf16 v[22:25], v[228:231], v[212:215], v[22:25]
	v_mfma_f32_16x16x32_bf16 v[18:21], v[236:239], v[212:215], v[18:21]
	v_mfma_f32_16x16x32_bf16 v[6:9], v[228:231], v[220:223], v[6:9]
	v_mfma_f32_16x16x32_bf16 v[2:5], v[236:239], v[220:223], v[2:5]
	v_mfma_f32_16x16x32_bf16 v[54:57], v[232:235], v[200:203], v[54:57]
	v_mfma_f32_16x16x32_bf16 v[50:53], v[240:243], v[200:203], v[50:53]
	v_mfma_f32_16x16x32_bf16 v[38:41], v[232:235], v[208:211], v[38:41]
	v_mfma_f32_16x16x32_bf16 v[34:37], v[240:243], v[208:211], v[34:37]
	v_mfma_f32_16x16x32_bf16 v[22:25], v[232:235], v[216:219], v[22:25]
	v_mfma_f32_16x16x32_bf16 v[18:21], v[240:243], v[216:219], v[18:21]
	v_mfma_f32_16x16x32_bf16 v[6:9], v[232:235], v[224:227], v[6:9]
	v_mfma_f32_16x16x32_bf16 v[2:5], v[240:243], v[224:227], v[2:5]
	s_setprio 0
	s_add_i32 s61, s61, 2
	s_add_u32 s59, s59, 0x100
	s_addc_u32 s60, s60, 0
	s_cmp_gt_u32 s61, 17
	s_mov_b64 s[30:31], s[42:43]
	s_barrier
	s_cbranch_scc0 .LBB0_1410
	v_readlane_b32 s80, v254, 5
	v_readlane_b32 s81, v254, 6
	v_readlane_b32 s82, v254, 7
	v_readlane_b32 s83, v254, 8
	s_cmp_ge_i32 s58, 65
	s_cselect_b32 s68, 1, 0
	s_mul_i32 s69, s68, 65
	s_sub_i32 s69, s58, s69
	s_cmp_eq_u32 s69, 0
	s_cbranch_scc1 .LepiC_ctx
	s_add_i32 s69, s69, -1
	s_lshl_b32 s69, s69, 8
	s_lshl_b32 s70, s68, 14
	s_add_i32 s69, s69, s70
	s_lshl_b32 s69, s69, 12
	s_add_u32 s70, s80, s69
	s_addc_u32 s71, s81, 0
	s_mul_i32 s68, s68, 0x3000
	s_branch .LepiC_go

.LepiC_go:
	s_add_u32 s72, s6, s68
	s_addc_u32 s73, s7, 0
	s_add_u32 s72, s72, 0x2000
	s_addc_u32 s73, s73, 0
	v_lshl_or_b32 v154, s57, 8, v161
	v_lshlrev_b32_e32 v154, 2, v154
	v_mov_b32_e32 v155, 0
	v_lshl_add_u64 v[166:167], v[154:155], 0, s[72:73]
	global_load_dwordx4 v[228:231], v[166:167], off
	global_load_dwordx4 v[232:235], v[166:167], off offset:64
	global_load_dwordx4 v[236:239], v[166:167], off offset:512
	global_load_dwordx4 v[240:243], v[166:167], off offset:576
	v_lshl_add_u32 v154, v147, 12, v154
	v_lshl_add_u64 v[220:221], v[154:155], 0, s[70:71]
	v_mov_b64_e32 v[156:157], v[220:221]
	global_load_dwordx4 v[188:191], v[156:157], off
	global_load_dwordx4 v[192:195], v[156:157], off offset:64
	global_load_dwordx4 v[196:199], v[156:157], off offset:512
	global_load_dwordx4 v[200:203], v[156:157], off offset:576
	v_add_co_u32_e32 v158, vcc, 0x10000, v220
	s_nop 1
	v_addc_co_u32_e32 v159, vcc, 0, v221, vcc
	global_load_dwordx4 v[204:207], v[158:159], off
	global_load_dwordx4 v[208:211], v[158:159], off offset:64
	global_load_dwordx4 v[212:215], v[158:159], off offset:512
	global_load_dwordx4 v[216:219], v[158:159], off offset:576
	s_waitcnt vmcnt(4)
	v_pk_fma_f32 v[126:127], v[126:127], v[228:229], v[188:189]
	v_pk_fma_f32 v[128:129], v[128:129], v[230:231], v[190:191]
	v_pk_fma_f32 v[122:123], v[122:123], v[232:233], v[192:193]
	v_pk_fma_f32 v[124:125], v[124:125], v[234:235], v[194:195]
	v_pk_fma_f32 v[118:119], v[118:119], v[236:237], v[196:197]
	v_pk_fma_f32 v[120:121], v[120:121], v[238:239], v[198:199]
	v_pk_fma_f32 v[114:115], v[114:115], v[240:241], v[200:201]
	v_pk_fma_f32 v[116:117], v[116:117], v[242:243], v[202:203]
	global_store_dwordx4 v[156:157], v[126:129], off
	global_store_dwordx4 v[156:157], v[122:125], off offset:64
	global_store_dwordx4 v[156:157], v[118:121], off offset:512
	global_store_dwordx4 v[156:157], v[114:117], off offset:576
	v_add_co_u32_e32 v156, vcc, 0x20000, v220
	s_nop 1
	v_addc_co_u32_e32 v157, vcc, 0, v221, vcc
	global_load_dwordx4 v[126:129], v[156:157], off
	global_load_dwordx4 v[122:125], v[156:157], off offset:64
	global_load_dwordx4 v[118:121], v[156:157], off offset:512
	global_load_dwordx4 v[114:117], v[156:157], off offset:576
	s_waitcnt vmcnt(8)
	v_pk_fma_f32 v[110:111], v[110:111], v[228:229], v[204:205]
	v_pk_fma_f32 v[112:113], v[112:113], v[230:231], v[206:207]
	v_pk_fma_f32 v[106:107], v[106:107], v[232:233], v[208:209]
	v_pk_fma_f32 v[108:109], v[108:109], v[234:235], v[210:211]
	v_pk_fma_f32 v[102:103], v[102:103], v[236:237], v[212:213]
	v_pk_fma_f32 v[104:105], v[104:105], v[238:239], v[214:215]
	v_pk_fma_f32 v[98:99], v[98:99], v[240:241], v[216:217]
	v_pk_fma_f32 v[100:101], v[100:101], v[242:243], v[218:219]
	global_store_dwordx4 v[158:159], v[110:113], off
	global_store_dwordx4 v[158:159], v[106:109], off offset:64
	global_store_dwordx4 v[158:159], v[102:105], off offset:512
	global_store_dwordx4 v[158:159], v[98:101], off offset:576
	v_add_co_u32_e32 v158, vcc, 0x30000, v220
	s_nop 1
	v_addc_co_u32_e32 v159, vcc, 0, v221, vcc
	global_load_dwordx4 v[110:113], v[158:159], off
	global_load_dwordx4 v[106:109], v[158:159], off offset:64
	global_load_dwordx4 v[102:105], v[158:159], off offset:512
	global_load_dwordx4 v[98:101], v[158:159], off offset:576
	s_waitcnt vmcnt(8)
	v_pk_fma_f32 v[94:95], v[94:95], v[228:229], v[126:127]
	v_pk_fma_f32 v[96:97], v[96:97], v[230:231], v[128:129]
	v_pk_fma_f32 v[90:91], v[90:91], v[232:233], v[122:123]
	v_pk_fma_f32 v[92:93], v[92:93], v[234:235], v[124:125]
	v_pk_fma_f32 v[86:87], v[86:87], v[236:237], v[118:119]
	v_pk_fma_f32 v[88:89], v[88:89], v[238:239], v[120:121]
	v_pk_fma_f32 v[82:83], v[82:83], v[240:241], v[114:115]
	v_pk_fma_f32 v[84:85], v[84:85], v[242:243], v[116:117]
	global_store_dwordx4 v[156:157], v[94:97], off
	global_store_dwordx4 v[156:157], v[90:93], off offset:64
	global_store_dwordx4 v[156:157], v[86:89], off offset:512
	global_store_dwordx4 v[156:157], v[82:85], off offset:576
	v_add_co_u32_e32 v156, vcc, 0x80000, v220
	s_nop 1
	v_addc_co_u32_e32 v157, vcc, 0, v221, vcc
	global_load_dwordx4 v[94:97], v[156:157], off
	global_load_dwordx4 v[90:93], v[156:157], off offset:64
	global_load_dwordx4 v[86:89], v[156:157], off offset:512
	global_load_dwordx4 v[82:85], v[156:157], off offset:576
	s_waitcnt vmcnt(8)
;   __device__ __forceinline__ void operator()(const f32x4 (&acc)[2][2][4][2], const pg8::Unit& u, int wr, int wc, int fr, int fq) const {
;     ...
;       for (int m = 0; m < 4; ++m) { const int row = u.pm * 256 + ai * 128 + wr * 64 + m * 16 + fr;
; #pragma unroll
;         for (int bj = 0; bj < 2; ++bj)
; #pragma unroll
;           for (int n = 0; n < 2; ++n) f(row, u.pn * 256 + bj * 128 + wc * 32 + n * 16 + 4 * fq, acc[ai][bj][m][n]); }
	v_pk_fma_f32 v[78:79], v[78:79], v[228:229], v[110:111]
	v_pk_fma_f32 v[80:81], v[80:81], v[230:231], v[112:113]
	v_pk_fma_f32 v[74:75], v[74:75], v[232:233], v[106:107]
	v_pk_fma_f32 v[76:77], v[76:77], v[234:235], v[108:109]
	v_pk_fma_f32 v[70:71], v[70:71], v[236:237], v[102:103]
	v_pk_fma_f32 v[72:73], v[72:73], v[238:239], v[104:105]
	v_pk_fma_f32 v[66:67], v[66:67], v[240:241], v[98:99]
	v_pk_fma_f32 v[68:69], v[68:69], v[242:243], v[100:101]
	global_store_dwordx4 v[158:159], v[78:81], off
	global_store_dwordx4 v[158:159], v[74:77], off offset:64
	global_store_dwordx4 v[158:159], v[70:73], off offset:512
	global_store_dwordx4 v[158:159], v[66:69], off offset:576
	v_add_co_u32_e32 v158, vcc, 0x90000, v220
	s_nop 1
	v_addc_co_u32_e32 v159, vcc, 0, v221, vcc
	global_load_dwordx4 v[78:81], v[158:159], off
	global_load_dwordx4 v[74:77], v[158:159], off offset:64
	global_load_dwordx4 v[70:73], v[158:159], off offset:512
	global_load_dwordx4 v[66:69], v[158:159], off offset:576
	s_waitcnt vmcnt(8)
	v_pk_fma_f32 v[62:63], v[62:63], v[228:229], v[94:95]
	v_pk_fma_f32 v[64:65], v[64:65], v[230:231], v[96:97]
	v_pk_fma_f32 v[58:59], v[58:59], v[232:233], v[90:91]
	v_pk_fma_f32 v[60:61], v[60:61], v[234:235], v[92:93]
	v_pk_fma_f32 v[54:55], v[54:55], v[236:237], v[86:87]
	v_pk_fma_f32 v[56:57], v[56:57], v[238:239], v[88:89]
	v_pk_fma_f32 v[50:51], v[50:51], v[240:241], v[82:83]
	v_pk_fma_f32 v[52:53], v[52:53], v[242:243], v[84:85]
	global_store_dwordx4 v[156:157], v[62:65], off
	global_store_dwordx4 v[156:157], v[58:61], off offset:64
	global_store_dwordx4 v[156:157], v[54:57], off offset:512
	global_store_dwordx4 v[156:157], v[50:53], off offset:576
	v_add_co_u32_e32 v156, vcc, 0xa0000, v220
	s_nop 1
	v_addc_co_u32_e32 v157, vcc, 0, v221, vcc
	global_load_dwordx4 v[62:65], v[156:157], off
	global_load_dwordx4 v[58:61], v[156:157], off offset:64
	global_load_dwordx4 v[54:57], v[156:157], off offset:512
	global_load_dwordx4 v[50:53], v[156:157], off offset:576
	s_waitcnt vmcnt(8)
	v_pk_fma_f32 v[46:47], v[46:47], v[228:229], v[78:79]
	v_pk_fma_f32 v[48:49], v[48:49], v[230:231], v[80:81]
	v_pk_fma_f32 v[42:43], v[42:43], v[232:233], v[74:75]
	v_pk_fma_f32 v[44:45], v[44:45], v[234:235], v[76:77]
	v_pk_fma_f32 v[38:39], v[38:39], v[236:237], v[70:71]
	v_pk_fma_f32 v[40:41], v[40:41], v[238:239], v[72:73]
	v_pk_fma_f32 v[34:35], v[34:35], v[240:241], v[66:67]
	v_pk_fma_f32 v[36:37], v[36:37], v[242:243], v[68:69]
	global_store_dwordx4 v[158:159], v[46:49], off
	global_store_dwordx4 v[158:159], v[42:45], off offset:64
	global_store_dwordx4 v[158:159], v[38:41], off offset:512
	global_store_dwordx4 v[158:159], v[34:37], off offset:576
	v_add_co_u32_e32 v158, vcc, 0xb0000, v220
	s_nop 1
	v_addc_co_u32_e32 v159, vcc, 0, v221, vcc
	global_load_dwordx4 v[46:49], v[158:159], off
	global_load_dwordx4 v[42:45], v[158:159], off offset:64
	global_load_dwordx4 v[38:41], v[158:159], off offset:512
	global_load_dwordx4 v[34:37], v[158:159], off offset:576
	s_waitcnt vmcnt(8)
	v_pk_fma_f32 v[30:31], v[30:31], v[228:229], v[62:63]
	v_pk_fma_f32 v[32:33], v[32:33], v[230:231], v[64:65]
	v_pk_fma_f32 v[26:27], v[26:27], v[232:233], v[58:59]
	v_pk_fma_f32 v[28:29], v[28:29], v[234:235], v[60:61]
	v_pk_fma_f32 v[22:23], v[22:23], v[236:237], v[54:55]
	v_pk_fma_f32 v[24:25], v[24:25], v[238:239], v[56:57]
	v_pk_fma_f32 v[18:19], v[18:19], v[240:241], v[50:51]
	v_pk_fma_f32 v[20:21], v[20:21], v[242:243], v[52:53]
	global_store_dwordx4 v[156:157], v[30:33], off
	global_store_dwordx4 v[156:157], v[26:29], off offset:64
	global_store_dwordx4 v[156:157], v[22:25], off offset:512
	global_store_dwordx4 v[156:157], v[18:21], off offset:576
	s_waitcnt vmcnt(4)
	v_pk_fma_f32 v[14:15], v[14:15], v[228:229], v[46:47]
	v_pk_fma_f32 v[16:17], v[16:17], v[230:231], v[48:49]
	v_pk_fma_f32 v[10:11], v[10:11], v[232:233], v[42:43]
	v_pk_fma_f32 v[12:13], v[12:13], v[234:235], v[44:45]
	v_pk_fma_f32 v[6:7], v[6:7], v[236:237], v[38:39]
	v_pk_fma_f32 v[8:9], v[8:9], v[238:239], v[40:41]
	v_pk_fma_f32 v[2:3], v[2:3], v[240:241], v[34:35]
	v_pk_fma_f32 v[4:5], v[4:5], v[242:243], v[36:37]
	global_store_dwordx4 v[158:159], v[14:17], off
	global_store_dwordx4 v[158:159], v[10:13], off offset:64
	global_store_dwordx4 v[158:159], v[6:9], off offset:512
	global_store_dwordx4 v[158:159], v[2:5], off offset:576
.LepiC_done:
	s_mov_b64 s[30:31], exec
	s_branch .LBB0_1402

; __device__ __forceinline__ void ph_pre(const P& p, char* smem) {
;     ...
;       int kq = tid >> 6, col = cgp * 64 + (tid & 63); const float* w = p.mod_w + (size_t)l * 1024 * 3072 + col;
;       float a0 = 0.f, a1 = 0.f, a2 = 0.f;
;       for (int k = kq * 128; k < kq * 128 + 128; k++) { float wv = w[(size_t)k * 3072]; a0 += sm[k] * wv; a1 += sm[1024 + k] * wv; a2 += sm[2048 + k] * wv; }
;       float* red = sm + 3072; red[tid * 3] = a0; red[tid * 3 + 1] = a1; red[tid * 3 + 2] = a2;
;       __syncthreads();
;       if (tid < 64) { float bias = p.mod_b[(size_t)l * 3072 + col];
;         for (int cnd = 0; cnd < 3; cnd++) { float s = bias; for (int q = 0; q < 8; q++) s += red[(q * 64 + tid) * 3 + cnd]; p.MOD[(size_t)(l * 3 + cnd) * 3072 + col] = s; } }
.LBB0_1923:
	s_mov_b64 s[12:13], 0x3000
	global_load_dword v24, v[10:11], off
	v_lshl_add_u64 v[10:11], v[10:11], 0, s[12:13]
	global_load_dword v25, v[10:11], off
	v_lshl_add_u64 v[10:11], v[10:11], 0, s[12:13]
	global_load_dword v26, v[10:11], off
	v_lshl_add_u64 v[10:11], v[10:11], 0, s[12:13]
	global_load_dword v27, v[10:11], off
	v_lshl_add_u64 v[10:11], v[10:11], 0, s[12:13]
	global_load_dword v28, v[10:11], off
	v_lshl_add_u64 v[10:11], v[10:11], 0, s[12:13]
	global_load_dword v29, v[10:11], off
	v_lshl_add_u64 v[10:11], v[10:11], 0, s[12:13]
	global_load_dword v30, v[10:11], off
	v_lshl_add_u64 v[10:11], v[10:11], 0, s[12:13]
	global_load_dword v31, v[10:11], off
	v_lshl_add_u64 v[10:11], v[10:11], 0, s[12:13]
	global_load_dword v32, v[10:11], off
	v_lshl_add_u64 v[10:11], v[10:11], 0, s[12:13]
	global_load_dword v33, v[10:11], off
	v_lshl_add_u64 v[10:11], v[10:11], 0, s[12:13]
	global_load_dword v34, v[10:11], off
	v_lshl_add_u64 v[10:11], v[10:11], 0, s[12:13]
	global_load_dword v35, v[10:11], off
	v_lshl_add_u64 v[10:11], v[10:11], 0, s[12:13]
	global_load_dword v36, v[10:11], off
	v_lshl_add_u64 v[10:11], v[10:11], 0, s[12:13]
	global_load_dword v37, v[10:11], off
	v_lshl_add_u64 v[10:11], v[10:11], 0, s[12:13]
	global_load_dword v38, v[10:11], off
	v_lshl_add_u64 v[10:11], v[10:11], 0, s[12:13]
	global_load_dword v39, v[10:11], off
	v_lshl_add_u64 v[10:11], v[10:11], 0, s[12:13]
	ds_read_b128 v[40:43], v9 offset:0
	ds_read_b128 v[44:47], v9 offset:16
	ds_read_b128 v[48:51], v9 offset:32
	ds_read_b128 v[52:55], v9 offset:48
	ds_read_b128 v[56:59], v9 offset:4096
	ds_read_b128 v[60:63], v9 offset:4112
	ds_read_b128 v[64:67], v9 offset:4128
	ds_read_b128 v[68:71], v9 offset:4144
	ds_read_b128 v[72:75], v9 offset:8192
	ds_read_b128 v[76:79], v9 offset:8208
	ds_read_b128 v[80:83], v9 offset:8224
	ds_read_b128 v[84:87], v9 offset:8240
	v_add_u32_e32 v19, 16, v19
	v_cmp_ge_i32_e32 vcc, v19, v14
	v_add_u32_e32 v9, 64, v9
	s_or_b64 s[6:7], vcc, s[6:7]
	s_waitcnt lgkmcnt(0)
	s_waitcnt vmcnt(15)
	v_fmac_f32_e32 v12, v24, v40
	v_fmac_f32_e32 v13, v24, v56
	v_fmac_f32_e32 v0, v24, v72
	s_waitcnt vmcnt(14)
	v_fmac_f32_e32 v12, v25, v41
	v_fmac_f32_e32 v13, v25, v57
	v_fmac_f32_e32 v0, v25, v73
	s_waitcnt vmcnt(13)
	v_fmac_f32_e32 v12, v26, v42
	v_fmac_f32_e32 v13, v26, v58
	v_fmac_f32_e32 v0, v26, v74
	s_waitcnt vmcnt(12)
	v_fmac_f32_e32 v12, v27, v43
	v_fmac_f32_e32 v13, v27, v59
	v_fmac_f32_e32 v0, v27, v75
	s_waitcnt vmcnt(11)
	v_fmac_f32_e32 v12, v28, v44
	v_fmac_f32_e32 v13, v28, v60
	v_fmac_f32_e32 v0, v28, v76
	s_waitcnt vmcnt(10)
	v_fmac_f32_e32 v12, v29, v45
	v_fmac_f32_e32 v13, v29, v61
	v_fmac_f32_e32 v0, v29, v77
	s_waitcnt vmcnt(9)
	v_fmac_f32_e32 v12, v30, v46
	v_fmac_f32_e32 v13, v30, v62
	v_fmac_f32_e32 v0, v30, v78
	s_waitcnt vmcnt(8)
	v_fmac_f32_e32 v12, v31, v47
	v_fmac_f32_e32 v13, v31, v63
	v_fmac_f32_e32 v0, v31, v79
	s_waitcnt vmcnt(7)
	v_fmac_f32_e32 v12, v32, v48
	v_fmac_f32_e32 v13, v32, v64
	v_fmac_f32_e32 v0, v32, v80
	s_waitcnt vmcnt(6)
	v_fmac_f32_e32 v12, v33, v49
	v_fmac_f32_e32 v13, v33, v65
	v_fmac_f32_e32 v0, v33, v81
	s_waitcnt vmcnt(5)
	v_fmac_f32_e32 v12, v34, v50
	v_fmac_f32_e32 v13, v34, v66
	v_fmac_f32_e32 v0, v34, v82
	s_waitcnt vmcnt(4)
	v_fmac_f32_e32 v12, v35, v51
	v_fmac_f32_e32 v13, v35, v67
	v_fmac_f32_e32 v0, v35, v83
	s_waitcnt vmcnt(3)
	v_fmac_f32_e32 v12, v36, v52
	v_fmac_f32_e32 v13, v36, v68
	v_fmac_f32_e32 v0, v36, v84
	s_waitcnt vmcnt(2)
	v_fmac_f32_e32 v12, v37, v53
	v_fmac_f32_e32 v13, v37, v69
	v_fmac_f32_e32 v0, v37, v85
	s_waitcnt vmcnt(1)
	v_fmac_f32_e32 v12, v38, v54
	v_fmac_f32_e32 v13, v38, v70
	v_fmac_f32_e32 v0, v38, v86
	s_waitcnt vmcnt(0)
	v_fmac_f32_e32 v12, v39, v55
	v_fmac_f32_e32 v13, v39, v71
	v_fmac_f32_e32 v0, v39, v87
	s_andn2_b64 exec, exec, s[6:7]
	s_cbranch_execnz .LBB0_1923
	s_or_b64 exec, exec, s[6:7]
	v_add_u32_e32 v9, 0x3000, v18
	ds_write2_b32 v9, v12, v13 offset1:1
	ds_write_b32 v18, v0 offset:12296
	s_waitcnt lgkmcnt(0)
	s_barrier
	s_and_saveexec_b64 s[6:7], s[42:43]
	s_cbranch_execz .LBB0_1926
	v_readlane_b32 s44, v254, 9
	s_mul_i32 s9, s8, 0x3000
	v_readlane_b32 s56, v254, 21
	v_readlane_b32 s57, v254, 22
	s_add_u32 s12, s56, s9
	s_addc_u32 s13, s57, 0
	v_lshlrev_b32_e32 v0, 2, v8
	global_load_dword v19, v0, s[12:13]
	v_add_u32_e32 v12, 0x3300, v18
	v_add_u32_e32 v20, 0x3600, v18
	v_add_u32_e32 v22, 0x3900, v18
	v_add_u32_e32 v24, 0x3c00, v18
	v_add_u32_e32 v26, 0x3f00, v18
	v_add_u32_e32 v28, 0x4200, v18
	v_add_u32_e32 v30, 0x4500, v18
	v_add_u32_e32 v38, 8, v18
	ds_read2_b32 v[8:9], v9 offset1:1
	ds_read2_b32 v[12:13], v12 offset1:1
	ds_read2_b32 v[20:21], v20 offset1:1
	ds_read2_b32 v[22:23], v22 offset1:1
	ds_read2_b32 v[24:25], v24 offset1:1
	ds_read2_b32 v[26:27], v26 offset1:1
	ds_read2_b32 v[28:29], v28 offset1:1
	ds_read2_b32 v[30:31], v30 offset1:1
	ds_read2st64_b32 v[32:33], v38 offset0:48 offset1:51
	ds_read2st64_b32 v[34:35], v38 offset0:54 offset1:57
	ds_read2st64_b32 v[36:37], v38 offset0:60 offset1:63
	ds_read2st64_b32 v[38:39], v38 offset0:66 offset1:69
	v_lshl_add_u64 v[10:11], s[20:21], 0, v[0:1]
	s_mul_i32 s8, s8, 3
	s_and_b32 s8, s8, 0xffff
	s_mul_i32 s28, s8, 0x3000
	v_lshl_add_u64 v[10:11], v[10:11], 0, s[28:29]
	s_movk_i32 s8, 0x3000
	v_add_co_u32_e32 v40, vcc, s8, v10
	v_readlane_b32 s45, v254, 10
	s_nop 0
	v_addc_co_u32_e32 v41, vcc, 0, v11, vcc
	v_add_co_u32_e32 v42, vcc, 0x6000, v10
	v_readlane_b32 s46, v254, 11
	v_readlane_b32 s47, v254, 12
	v_readlane_b32 s48, v254, 13
	v_readlane_b32 s49, v254, 14
	v_readlane_b32 s50, v254, 15
	v_readlane_b32 s51, v254, 16
	v_readlane_b32 s52, v254, 17
	v_readlane_b32 s53, v254, 18
	v_readlane_b32 s54, v254, 19
	v_readlane_b32 s55, v254, 20
	v_readlane_b32 s58, v254, 23
	v_readlane_b32 s59, v254, 24
	v_addc_co_u32_e32 v43, vcc, 0, v11, vcc
	s_waitcnt vmcnt(0) lgkmcnt(11)
	v_add_f32_e32 v0, v19, v8
	v_add_f32_e32 v8, v19, v9
	s_waitcnt lgkmcnt(3)
	v_add_f32_e32 v9, v19, v32
	v_add_f32_e32 v0, v0, v12
	v_add_f32_e32 v8, v8, v13
	v_add_f32_e32 v9, v9, v33
	v_add_f32_e32 v0, v0, v20
	v_add_f32_e32 v8, v8, v21
	s_waitcnt lgkmcnt(2)
	v_add_f32_e32 v9, v9, v34
	v_add_f32_e32 v0, v0, v22
	v_add_f32_e32 v8, v8, v23
	v_add_f32_e32 v9, v9, v35
	v_add_f32_e32 v0, v0, v24
	v_add_f32_e32 v8, v8, v25
	s_waitcnt lgkmcnt(1)
	v_add_f32_e32 v9, v9, v36
	v_add_f32_e32 v0, v0, v26
	v_add_f32_e32 v8, v8, v27
	v_add_f32_e32 v9, v9, v37
	v_add_f32_e32 v0, v0, v28
	v_add_f32_e32 v8, v8, v29
	s_waitcnt lgkmcnt(0)
	v_add_f32_e32 v9, v9, v38
	v_add_f32_e32 v0, v0, v30
	v_add_f32_e32 v8, v8, v31
	v_add_f32_e32 v9, v9, v39
	global_store_dword v[10:11], v0, off
	global_store_dword v[40:41], v8, off
	global_store_dword v[42:43], v9, off
